# mqk: 4x4 block weights staged in LDS (ds_read), vmcnt waits of the channel loop re-derived from register dataflow so next-step rows stay in flight
# baseline (speedup 1.0000x reference)
; __device__ __forceinline__ void unpack8(u32x4 w, float* f) { f[0] = bflo(w.x); f[1] = bfhi(w.x); f[2] = bflo(w.y); f[3] = bfhi(w.y); f[4] = bflo(w.z); f[5] = bfhi(w.z); f[6] = bflo(w.w); f[7] = bfhi(w.w); }
; __device__ void mqk_phase(const Params& p, unsigned char* smem) {
;     ...
;     for (int tile = blockIdx.x; tile < 256; tile += gridDim.x) {
;         const int row0 = tile * 64;
;         f32x4 acc[4];
; #pragma unroll
;         for (int m = 0; m < 4; ++m) acc[m] = (f32x4){0.f, 0.f, 0.f, 0.f};
;         for (int ks = 0; ks < 8; ++ks) {
;             const int c0 = 256 * wave + 32 * ks + 8 * (lane >> 4);
;             float cw[4][8], cbv[8];
; #pragma unroll
;             for (int j = 0; j < 4; ++j) { const f32x4 a = *(const f32x4*)(p.in[10] + j * 2048 + c0), b = *(const f32x4*)(p.in[10] + j * 2048 + c0 + 4);
; #pragma unroll
;                 for (int i = 0; i < 4; ++i) { cw[j][i] = a[i]; cw[j][4 + i] = b[i]; } }
;             { const f32x4 a = *(const f32x4*)(p.in[11] + c0), b = *(const f32x4*)(p.in[11] + c0 + 4);
; #pragma unroll
;               for (int i = 0; i < 4; ++i) { cbv[i] = a[i]; cbv[4 + i] = b[i]; } }
;             const bf16x8 bq = *(const bf16x8*)(WG + (size_t)(lane & 15) * 6144 + c0), bk = *(const bf16x8*)(WG + (size_t)(lane & 15) * 6144 + 2048 + c0), bv = *(const bf16x8*)(WG + (size_t)(lane & 15) * 6144 + 4096 + c0);
;             const float* wqp = p.in[12] + (size_t)(c0 >> 2) * 16; const float* wkp = p.in[13] + (size_t)(c0 >> 2) * 16; const float* wvp = p.in[14] + (size_t)(c0 >> 2) * 16;
;             u32x4 xraw[4];
;     ...
;             MQ_LOAD(xraw, 0);
; #pragma unroll
;             for (int m = 0; m < 4; ++m) {
;                 const int tk = row0 + 16 * m + (lane & 15);
;                 u32x4 xnx[4];
;                 if (m < 3) MQ_LOAD(xnx, m + 1);
;                 float xmc[8], xcur[8];
; #pragma unroll
;                 for (int i = 0; i < 8; ++i) xmc[i] = cbv[i];
; #pragma unroll
;                 for (int j = 0; j < 4; ++j) { float xv[8]; unpack8(xraw[j], xv);
; #pragma unroll
;                     for (int i = 0; i < 8; ++i) { xmc[i] += cw[j][i] * xv[i]; if (j == 3) xcur[i] = xv[i]; } }
.LBB0_299:
	v_and_b32_e32 v118, 0x3ff, v0
	v_lshlrev_b32_e32 v118, 4, v118
	v_add_u32_e32 v119, 0x2000, v118
	v_add_u32_e32 v120, 0x4000, v118
	v_add_u32_e32 v121, 0x6000, v118
	global_load_dwordx4 v[70:73], v118, s[80:81]
	global_load_dwordx4 v[74:77], v119, s[80:81]
	global_load_dwordx4 v[78:81], v120, s[80:81]
	global_load_dwordx4 v[82:85], v121, s[80:81]
	global_load_dwordx4 v[86:89], v118, s[76:77]
	global_load_dwordx4 v[90:93], v119, s[76:77]
	global_load_dwordx4 v[94:97], v120, s[76:77]
	global_load_dwordx4 v[98:101], v121, s[76:77]
	global_load_dwordx4 v[102:105], v118, s[78:79]
	global_load_dwordx4 v[106:109], v119, s[78:79]
	global_load_dwordx4 v[110:113], v120, s[78:79]
	global_load_dwordx4 v[114:117], v121, s[78:79]
	s_waitcnt vmcnt(0)
	ds_write_b128 v118, v[70:73] offset:32768
	ds_write_b128 v119, v[74:77] offset:32768
	ds_write_b128 v120, v[78:81] offset:32768
	ds_write_b128 v121, v[82:85] offset:32768
	v_add_u32_e32 v118, 0x10000, v118
	v_add_u32_e32 v119, 0x10000, v119
	v_add_u32_e32 v120, 0x10000, v120
	v_add_u32_e32 v121, 0x10000, v121
	ds_write_b128 v118, v[86:89]
	ds_write_b128 v119, v[90:93]
	ds_write_b128 v120, v[94:97]
	ds_write_b128 v121, v[98:101]
	ds_write_b128 v118, v[102:105] offset:32768
	ds_write_b128 v119, v[106:109] offset:32768
	ds_write_b128 v120, v[110:113] offset:32768
	ds_write_b128 v121, v[114:117] offset:32768
	s_waitcnt lgkmcnt(0)
	s_barrier
	s_lshl_b32 s2, s50, 6
	v_or_b32_e32 v2, s2, v229
	v_ashrrev_i32_e32 v3, 31, v2
	v_bitop3_b32 v5, s2, v232, v229 bitop3:0xc8
	v_or_b32_e32 v4, 16, v2
	v_lshlrev_b64 v[174:175], 12, v[2:3]
	v_lshlrev_b64 v[6:7], 11, v[2:3]
	v_or_b32_e32 v8, 32, v2
	v_or_b32_e32 v2, 48, v2
	v_cmp_lt_u32_e32 vcc, 2, v5
	v_cmp_lt_u32_e64 s[2:3], 1, v5
	v_cmp_ne_u32_e64 s[4:5], 0, v5
	v_ashrrev_i32_e32 v5, 31, v4
	v_ashrrev_i32_e32 v9, 31, v8
	v_ashrrev_i32_e32 v3, 31, v2
	v_lshlrev_b64 v[188:189], 12, v[4:5]
	v_lshlrev_b64 v[196:197], 12, v[8:9]
	v_lshlrev_b64 v[4:5], 11, v[4:5]
	v_lshlrev_b64 v[204:205], 12, v[2:3]
	v_lshlrev_b64 v[8:9], 11, v[8:9]
	v_lshlrev_b64 v[2:3], 11, v[2:3]
	v_lshl_add_u64 v[176:177], v[174:175], 0, s[14:15]
	v_lshl_add_u64 v[178:179], v[174:175], 0, s[16:17]
	v_lshl_add_u64 v[180:181], v[174:175], 0, s[18:19]
	v_lshl_add_u64 v[182:183], v[174:175], 0, s[20:21]
	v_lshl_add_u64 v[184:185], v[174:175], 0, s[22:23]
	v_lshl_add_u64 v[186:187], v[174:175], 0, s[24:25]
	v_lshl_add_u64 v[190:191], v[174:175], 0, s[26:27]
	v_lshl_add_u64 v[192:193], v[174:175], 0, s[28:29]
	v_lshl_add_u64 v[194:195], v[174:175], 0, s[30:31]
	v_lshl_add_u64 v[198:199], v[174:175], 0, s[34:35]
	v_lshl_add_u64 v[200:201], v[174:175], 0, s[36:37]
	v_lshl_add_u64 v[202:203], v[174:175], 0, s[38:39]
	v_lshlrev_b64 v[206:207], 1, v[6:7]
	v_lshlrev_b64 v[208:209], 1, v[4:5]
	v_lshlrev_b64 v[210:211], 1, v[8:9]
	v_lshlrev_b64 v[212:213], 1, v[2:3]
	s_mov_b32 s51, 0
	v_mov_b32_e32 v66, v163
	v_mov_b32_e32 v67, v163
	v_mov_b32_e32 v68, v163
	v_mov_b32_e32 v69, v163
	v_mov_b32_e32 v62, v163
	v_mov_b32_e32 v63, v163
	v_mov_b32_e32 v64, v163
	v_mov_b32_e32 v65, v163
	v_mov_b32_e32 v2, v163
	v_mov_b32_e32 v3, v163
	v_mov_b32_e32 v4, v163
	v_mov_b32_e32 v5, v163
	v_mov_b32_e32 v6, v163
	v_mov_b32_e32 v7, v163
	v_mov_b32_e32 v8, v163
	v_mov_b32_e32 v9, v163
	s_branch .LBB0_301
.LBB0_300:
	s_or_b64 exec, exec, s[6:7]
	v_lshl_add_u64 v[70:71], v[224:225], 0, v[174:175]
	global_load_dwordx4 v[98:101], v[70:71], off
	v_lshrrev_b32_e32 v70, 2, v162
	v_mov_b32_e32 v71, v163
	v_lshlrev_b64 v[70:71], 6, v[70:71]
	v_add_u32_e32 v218, 0x8000, v70
	ds_read_b128 v[114:117], v218
	ds_read_b128 v[110:113], v218 offset:16
	s_nop 0
	v_add_u32_e32 v222, 0x18000, v70
	ds_read_b128 v[118:121], v218 offset:32784
	ds_read_b128 v[130:133], v218 offset:32768
	ds_read_b128 v[126:129], v222
	ds_read_b128 v[122:125], v222 offset:16
	ds_read_b128 v[106:109], v218 offset:32
	ds_read_b128 v[102:105], v218 offset:48
	s_nop 0
	s_waitcnt vmcnt(1)
	v_lshlrev_b32_e32 v134, 16, v90
	v_and_b32_e32 v135, 0xffff0000, v90
	v_lshl_add_u64 v[70:71], v[224:225], 0, v[182:183]
	v_lshl_add_u64 v[72:73], v[224:225], 0, v[184:185]
	v_lshl_add_u64 v[82:83], v[224:225], 0, v[186:187]
	v_lshl_add_u64 v[84:85], v[224:225], 0, v[188:189]
	v_lshlrev_b32_e32 v136, 16, v86
	v_and_b32_e32 v137, 0xffff0000, v86
	v_pk_fma_f32 v[134:135], v[46:47], v[134:135], v[58:59]
	global_load_dwordx4 v[78:81], v[70:71], off
	global_load_dwordx4 v[74:77], v[72:73], off
	s_nop 0
	global_load_dwordx4 v[70:73], v[82:83], off
	s_nop 0
	global_load_dwordx4 v[82:85], v[84:85], off
	v_pk_fma_f32 v[152:153], v[50:51], v[136:137], v[134:135]
	ds_read_b128 v[142:145], v218 offset:32816
	ds_read_b128 v[146:149], v218 offset:32800
	ds_read_b128 v[134:137], v222 offset:48
	ds_read_b128 v[138:141], v222 offset:32
	v_lshlrev_b32_e32 v150, 16, v94
	v_and_b32_e32 v151, 0xffff0000, v94
	v_pk_fma_f32 v[150:151], v[54:55], v[150:151], v[152:153]
	v_lshlrev_b32_e32 v162, 1, v162
	v_lshl_add_u64 v[216:217], s[10:11], 0, v[162:163]
	v_lshl_add_u64 v[214:215], s[12:13], 0, v[162:163]
	s_add_i32 s51, s51, 1
	s_cmp_eq_u32 s51, 8
	s_nop 0
	s_waitcnt vmcnt(4)
	v_lshlrev_b32_e32 v158, 16, v98
	v_and_b32_e32 v159, 0xffff0000, v98
	v_pk_fma_f32 v[150:151], v[42:43], v[158:159], v[150:151]
	v_lshlrev_b32_e32 v98, 16, v99
	v_mul_f32_e32 v86, 0xbfb8aa3b, v150
	v_mul_f32_e32 v90, 0xbfb8aa3b, v151
	v_exp_f32_e32 v86, v86
	v_exp_f32_e32 v90, v90
	s_nop 0
	s_waitcnt lgkmcnt(11)
	v_mov_b32_e32 v152, v114
	s_nop 0
	s_waitcnt lgkmcnt(10)
; __device__ __forceinline__ void unpack8(u32x4 w, float* f) { f[0] = bflo(w.x); f[1] = bfhi(w.x); f[2] = bflo(w.y); f[3] = bfhi(w.y); f[4] = bflo(w.z); f[5] = bfhi(w.z); f[6] = bflo(w.w); f[7] = bfhi(w.w); }
; __device__ __forceinline__ float fsig0(float x) { return __builtin_amdgcn_rcpf(1.0f + __expf(-x)); }
; __device__ void mqk_phase(const Params& p, unsigned char* smem) {
;     ...
;                 for (int j = 0; j < 4; ++j) { float xv[8]; unpack8(xraw[j], xv);
; #pragma unroll
;                     for (int i = 0; i < 8; ++i) { xmc[i] += cw[j][i] * xv[i]; if (j == 3) xcur[i] = xv[i]; } }
;                 if (m < 3) {
; #pragma unroll
;                     for (int j = 0; j < 4; ++j) xraw[j] = xnx[j]; }
; #pragma unroll
;                 for (int i = 0; i < 8; ++i) xmc[i] = xmc[i] * fsig0(xmc[i]);
;                 float qv[8], kv[8], vv[8];
; #pragma unroll
;                 for (int bb = 0; bb < 2; ++bb)
; #pragma unroll
;                     for (int jj = 0; jj < 4; ++jj) { float aq = 0.f, ak = 0.f, av = 0.f;
; #pragma unroll
;                         for (int ii = 0; ii < 4; ++ii) { aq += xmc[4 * bb + ii] * wqp[bb * 16 + ii * 4 + jj]; ak += xmc[4 * bb + ii] * wkp[bb * 16 + ii * 4 + jj]; av += xcur[4 * bb + ii] * wvp[bb * 16 + ii * 4 + jj]; }
;                         qv[4 * bb + jj] = aq; kv[4 * bb + jj] = ak; vv[4 * bb + jj] = av; }
	v_mov_b32_e32 v153, v110
	v_add_f32_e32 v86, 1.0, v86
	v_add_f32_e32 v90, 1.0, v90
	v_rcp_f32_e32 v226, v86
	v_rcp_f32_e32 v227, v90
	v_mov_b32_e32 v110, v115
	v_mov_b32_e32 v114, v116
	v_mov_b32_e32 v115, v112
	v_pk_mul_f32 v[110:111], v[110:111], v[158:159]
	v_pk_mul_f32 v[114:115], v[114:115], v[158:159]
	s_nop 0
	s_waitcnt lgkmcnt(5)
	v_mov_b32_e32 v160, v106
	v_add_f32_e32 v106, 0, v110
	v_add_f32_e32 v110, 0, v114
	v_mov_b32_e32 v156, v126
	v_mov_b32_e32 v157, v122
	v_add_f32_e32 v90, v106, v111
	v_add_f32_e32 v106, v110, v115
	v_pk_mul_f32 v[110:111], v[150:151], v[226:227]
	v_mov_b32_e32 v154, v130
	v_mov_b32_e32 v155, v118
	v_mov_b32_e32 v118, v131
	v_pk_mul_f32 v[152:153], v[152:153], v[158:159]
	v_pk_mul_f32 v[150:151], v[156:157], v[110:111]
	v_mov_b32_e32 v122, v127
	v_add_f32_e32 v94, 0, v152
	v_pk_mul_f32 v[114:115], v[154:155], v[110:111]
	v_pk_mul_f32 v[118:119], v[110:111], v[118:119]
	v_add_f32_e32 v112, 0, v150
	v_and_b32_e32 v99, 0xffff0000, v99
	v_add_f32_e32 v86, v94, v153
	v_pk_mul_f32 v[122:123], v[110:111], v[122:123]
	v_add_f32_e32 v94, 0, v114
	v_add_f32_e32 v114, 0, v118
	v_add_f32_e32 v112, v151, v112
	s_nop 0
	s_waitcnt lgkmcnt(4)
	v_mov_b32_e32 v161, v102
	ds_read_b128 v[150:153], v218 offset:80
	ds_read_b128 v[154:157], v218 offset:64
	v_add_f32_e32 v116, 0, v122
	v_add_f32_e32 v122, v115, v94
	v_add_f32_e32 v119, v114, v119
	v_pk_mul_f32 v[114:115], v[160:161], v[98:99]
	v_mov_b32_e32 v102, v107
	v_mov_b32_e32 v130, v132
	v_mov_b32_e32 v131, v120
	v_add_f32_e32 v86, v86, v114
	v_pk_mul_f32 v[102:103], v[102:103], v[98:99]
	v_mov_b32_e32 v126, v128
	v_pk_mul_f32 v[130:131], v[110:111], v[130:131]
	v_add_f32_e32 v128, v86, v115
	v_add_f32_e32 v86, v90, v102
	v_lshlrev_b32_e32 v90, 16, v91
	v_and_b32_e32 v91, 0xffff0000, v91
	v_add_f32_e32 v120, 0, v130
	v_add_f32_e32 v130, v86, v103
	v_pk_fma_f32 v[90:91], v[48:49], v[90:91], v[60:61]
	v_lshlrev_b32_e32 v86, 16, v87
	v_and_b32_e32 v87, 0xffff0000, v87
	v_pk_fma_f32 v[86:87], v[52:53], v[86:87], v[90:91]
	v_lshlrev_b32_e32 v90, 16, v95
	v_and_b32_e32 v91, 0xffff0000, v95
	v_pk_fma_f32 v[86:87], v[56:57], v[90:91], v[86:87]
	ds_read_b128 v[234:237], v218 offset:32848
	ds_read_b128 v[238:241], v218 offset:32832
	v_pk_fma_f32 v[86:87], v[44:45], v[98:99], v[86:87]
	v_add_f32_e32 v120, v120, v131
	v_mul_f32_e32 v90, 0xbfb8aa3b, v86
	v_exp_f32_e32 v91, v90
	v_mul_f32_e32 v90, 0xbfb8aa3b, v87
	v_exp_f32_e32 v95, v90
	ds_read_b128 v[242:245], v222 offset:80
	ds_read_b128 v[246:249], v222 offset:64
	v_add_f32_e32 v91, 1.0, v91
	v_rcp_f32_e32 v94, v91
	v_add_f32_e32 v91, 1.0, v95
	v_rcp_f32_e32 v95, v91
	v_mov_b32_e32 v127, v124
	v_add_f32_e32 v116, v116, v123
	v_mov_b32_e32 v90, v108
	v_pk_mul_f32 v[86:87], v[86:87], v[94:95]
	s_nop 0
	s_waitcnt lgkmcnt(8)
	v_mov_b32_e32 v94, v146
	v_mov_b32_e32 v95, v142
	v_pk_mul_f32 v[94:95], v[86:87], v[94:95]
	v_mov_b32_e32 v142, v147
	v_add_f32_e32 v94, v94, v122
	v_add_f32_e32 v131, v94, v95
	s_nop 0
	s_waitcnt lgkmcnt(6)
	v_mov_b32_e32 v94, v138
	v_mov_b32_e32 v95, v134
	v_pk_mul_f32 v[94:95], v[86:87], v[94:95]
	v_mov_b32_e32 v134, v139
	v_add_f32_e32 v94, v112, v94
	v_add_f32_e32 v132, v94, v95
	v_pk_mul_f32 v[94:95], v[86:87], v[142:143]
	v_mov_b32_e32 v91, v104
	v_add_f32_e32 v94, v119, v94
	v_add_f32_e32 v138, v94, v95
	v_pk_mul_f32 v[94:95], v[86:87], v[134:135]
	v_mov_b32_e32 v102, v148
	v_mov_b32_e32 v103, v144
	v_pk_mul_f32 v[126:127], v[110:111], v[126:127]
	v_pk_mul_f32 v[90:91], v[90:91], v[98:99]
	v_add_f32_e32 v94, v116, v94
	v_pk_mul_f32 v[102:103], v[86:87], v[102:103]
	v_add_f32_e32 v118, 0, v126
	v_add_f32_e32 v90, v106, v90
	v_add_f32_e32 v134, v94, v95
	v_mov_b32_e32 v94, v140
	v_mov_b32_e32 v95, v136
	v_add_f32_e32 v102, v120, v102
	v_mov_b32_e32 v120, v133
	v_add_f32_e32 v118, v118, v127
	v_pk_mul_f32 v[94:95], v[86:87], v[94:95]
	v_add_f32_e32 v140, v90, v91
	v_pk_mul_f32 v[90:91], v[110:111], v[120:121]
	v_add_f32_e32 v94, v118, v94
	v_add_f32_e32 v90, 0, v90
	v_mov_b32_e32 v124, v129
	v_add_f32_e32 v139, v94, v95
	v_add_f32_e32 v94, v90, v91
	v_pk_mul_f32 v[90:91], v[110:111], v[124:125]
	v_mov_b32_e32 v112, v117
	v_add_f32_e32 v90, 0, v90
	v_add_f32_e32 v95, v90, v91
	v_pk_mul_f32 v[90:91], v[112:113], v[158:159]
	ds_read_b128 v[110:113], v218 offset:112
	ds_read_b128 v[114:117], v218 offset:96
	v_add_f32_e32 v90, 0, v90
	v_mov_b32_e32 v144, v149
	v_mov_b32_e32 v136, v141
	v_add_f32_e32 v135, v102, v103
	v_add_f32_e32 v102, v90, v91
	v_pk_mul_f32 v[90:91], v[86:87], v[144:145]
	v_pk_mul_f32 v[86:87], v[86:87], v[136:137]
	v_mov_b32_e32 v104, v109
	v_add_f32_e32 v86, v95, v86
	v_add_f32_e32 v133, v86, v87
	v_pk_mul_f32 v[86:87], v[104:105], v[98:99]
	v_add_f32_e32 v90, v94, v90
	v_add_f32_e32 v86, v102, v86
	ds_read_b128 v[102:105], v218 offset:32880
	ds_read_b128 v[106:109], v218 offset:32864
	ds_read_b128 v[118:121], v222 offset:112
	ds_read_b128 v[122:125], v222 offset:96
	v_add_f32_e32 v129, v90, v91
	v_add_f32_e32 v136, v86, v87
	v_lshlrev_b32_e32 v86, 16, v100
	v_and_b32_e32 v87, 0xffff0000, v100
	s_nop 0
	s_waitcnt lgkmcnt(10)
	v_mov_b32_e32 v90, v154
	v_mov_b32_e32 v91, v150
	v_pk_mul_f32 v[90:91], v[90:91], v[86:87]
	v_mov_b32_e32 v150, v155
	v_add_f32_e32 v90, 0, v90
	v_add_f32_e32 v100, v90, v91
	v_pk_mul_f32 v[90:91], v[150:151], v[86:87]
	v_lshlrev_b32_e32 v94, 16, v88
	v_add_f32_e32 v90, 0, v90
	v_add_f32_e32 v137, v90, v91
	v_lshlrev_b32_e32 v90, 16, v92
	v_and_b32_e32 v91, 0xffff0000, v92
	v_pk_fma_f32 v[90:91], v[22:23], v[90:91], v[38:39]
	v_and_b32_e32 v95, 0xffff0000, v88
	v_pk_fma_f32 v[90:91], v[26:27], v[94:95], v[90:91]
	v_lshlrev_b32_e32 v94, 16, v96
	v_and_b32_e32 v95, 0xffff0000, v96
	v_pk_fma_f32 v[90:91], v[30:31], v[94:95], v[90:91]
	v_mov_b32_e32 v94, v156
	v_pk_fma_f32 v[90:91], v[34:35], v[86:87], v[90:91]
	v_mov_b32_e32 v95, v152
	v_mul_f32_e32 v88, 0xbfb8aa3b, v90
	v_exp_f32_e32 v88, v88
	v_mul_f32_e32 v92, 0xbfb8aa3b, v91
	v_exp_f32_e32 v92, v92
	s_nop 0
	s_waitcnt lgkmcnt(8)
; __device__ __forceinline__ u32x4 pack8(const float* f) { u32x4 w; w.x = pk2(f[0], f[1]); w.y = pk2(f[2], f[3]); w.z = pk2(f[4], f[5]); w.w = pk2(f[6], f[7]); return w; }
; #define MFMA16(a, b, c) __builtin_amdgcn_mfma_f32_16x16x32_bf16((a), (b), (c), 0, 0, 0)
; __device__ __forceinline__ float fsig0(float x) { return __builtin_amdgcn_rcpf(1.0f + __expf(-x)); }
; __device__ void mqk_phase(const Params& p, unsigned char* smem) {
;     ...
;                 for (int i = 0; i < 8; ++i) xmc[i] = xmc[i] * fsig0(xmc[i]);
;                 float qv[8], kv[8], vv[8];
; #pragma unroll
;                 for (int bb = 0; bb < 2; ++bb)
; #pragma unroll
;                     for (int jj = 0; jj < 4; ++jj) { float aq = 0.f, ak = 0.f, av = 0.f;
; #pragma unroll
;                         for (int ii = 0; ii < 4; ++ii) { aq += xmc[4 * bb + ii] * wqp[bb * 16 + ii * 4 + jj]; ak += xmc[4 * bb + ii] * wkp[bb * 16 + ii * 4 + jj]; av += xcur[4 * bb + ii] * wvp[bb * 16 + ii * 4 + jj]; }
;                         qv[4 * bb + jj] = aq; kv[4 * bb + jj] = ak; vv[4 * bb + jj] = av; }
;                 const u32x4 qw = pack8(qv), kw = pack8(kv), vw = pack8(vv);
;                 acc[m] = MFMA16(as_frag(qw), bq, acc[m]); acc[m] = MFMA16(as_frag(kw), bk, acc[m]); acc[m] = MFMA16(as_frag(vw), bv, acc[m]);
; #pragma unroll
;                 for (int i = 0; i < 8; ++i) kv[i] *= 0.0625f;
;                 *(u32x4*)(Q + (size_t)tk * 2048 + c0) = qw; *(u32x4*)(KX + (size_t)tk * 2048 + c0) = pack8(kv);
;             }
	v_mov_b32_e32 v126, v240
	v_add_f32_e32 v88, 1.0, v88
	v_rcp_f32_e32 v98, v88
	v_add_f32_e32 v88, 1.0, v92
	v_rcp_f32_e32 v99, v88
	v_mov_b32_e32 v127, v236
	v_pk_mul_f32 v[94:95], v[94:95], v[86:87]
	v_mov_b32_e32 v236, v241
	v_pk_mul_f32 v[90:91], v[90:91], v[98:99]
	v_mov_b32_e32 v98, v238
	v_mov_b32_e32 v99, v234
	v_pk_mul_f32 v[98:99], v[90:91], v[98:99]
	v_mov_b32_e32 v234, v239
	v_add_f32_e32 v92, 0, v98
	v_add_f32_e32 v141, v92, v99
	s_nop 0
	s_waitcnt lgkmcnt(6)
	v_mov_b32_e32 v98, v246
	v_mov_b32_e32 v99, v242
	v_pk_mul_f32 v[98:99], v[90:91], v[98:99]
	v_mov_b32_e32 v242, v247
	v_add_f32_e32 v92, 0, v98
	v_add_f32_e32 v142, v92, v99
	v_pk_mul_f32 v[98:99], v[90:91], v[234:235]
	v_pk_mul_f32 v[126:127], v[90:91], v[126:127]
	v_add_f32_e32 v92, 0, v98
	v_add_f32_e32 v143, v92, v99
	v_pk_mul_f32 v[98:99], v[90:91], v[242:243]
	v_add_f32_e32 v88, 0, v94
	v_add_f32_e32 v92, 0, v98
	v_add_f32_e32 v144, v92, v99
	v_mov_b32_e32 v98, v248
	v_mov_b32_e32 v99, v244
	v_pk_mul_f32 v[98:99], v[90:91], v[98:99]
	v_add_f32_e32 v94, 0, v126
	v_add_f32_e32 v92, 0, v98
	v_add_f32_e32 v126, v94, v127
	v_add_f32_e32 v127, v92, v99
	v_add_f32_e32 v145, v88, v95
	v_lshlrev_b32_e32 v94, 16, v101
	v_and_b32_e32 v95, 0xffff0000, v101
	s_nop 0
	s_waitcnt lgkmcnt(4)
	v_mov_b32_e32 v98, v114
	v_mov_b32_e32 v99, v110
	v_pk_mul_f32 v[98:99], v[98:99], v[94:95]
	v_mov_b32_e32 v110, v115
	v_add_f32_e32 v88, v100, v98
	v_add_f32_e32 v100, v88, v99
	v_pk_mul_f32 v[98:99], v[110:111], v[94:95]
	v_lshlrev_b32_e32 v92, 16, v93
	v_add_f32_e32 v88, v137, v98
	v_and_b32_e32 v93, 0xffff0000, v93
	v_add_f32_e32 v101, v88, v99
	v_pk_fma_f32 v[92:93], v[24:25], v[92:93], v[40:41]
	v_lshlrev_b32_e32 v88, 16, v89
	v_and_b32_e32 v89, 0xffff0000, v89
	v_pk_fma_f32 v[88:89], v[28:29], v[88:89], v[92:93]
	v_lshlrev_b32_e32 v92, 16, v97
	v_and_b32_e32 v93, 0xffff0000, v97
	v_pk_fma_f32 v[88:89], v[32:33], v[92:93], v[88:89]
	v_mov_b32_e32 v244, v249
	v_pk_fma_f32 v[88:89], v[36:37], v[94:95], v[88:89]
	v_mov_b32_e32 v152, v157
	v_mul_f32_e32 v92, 0xbfb8aa3b, v88
	v_exp_f32_e32 v93, v92
	v_mul_f32_e32 v92, 0xbfb8aa3b, v89
	v_exp_f32_e32 v97, v92
	v_mov_b32_e32 v92, v116
	v_add_f32_e32 v93, 1.0, v93
	v_rcp_f32_e32 v96, v93
	v_add_f32_e32 v93, 1.0, v97
	v_rcp_f32_e32 v97, v93
	v_mov_b32_e32 v93, v112
	v_pk_mul_f32 v[92:93], v[92:93], v[94:95]
	v_pk_mul_f32 v[86:87], v[152:153], v[86:87]
	v_pk_mul_f32 v[88:89], v[88:89], v[96:97]
	s_nop 0
	s_waitcnt lgkmcnt(2)
	v_mov_b32_e32 v96, v106
	v_mov_b32_e32 v97, v102
	v_pk_mul_f32 v[96:97], v[88:89], v[96:97]
	v_mov_b32_e32 v102, v107
	v_add_f32_e32 v96, v141, v96
	v_add_f32_e32 v106, v96, v97
	s_nop 0
	s_waitcnt lgkmcnt(0)
	v_mov_b32_e32 v96, v122
	v_mov_b32_e32 v97, v118
	v_pk_mul_f32 v[96:97], v[88:89], v[96:97]
	v_mov_b32_e32 v118, v123
	v_add_f32_e32 v96, v142, v96
	v_add_f32_e32 v110, v96, v97
	v_pk_mul_f32 v[96:97], v[88:89], v[102:103]
	v_add_f32_e32 v92, v145, v92
	v_add_f32_e32 v96, v143, v96
	v_add_f32_e32 v102, v96, v97
	v_pk_mul_f32 v[96:97], v[88:89], v[118:119]
	v_mov_b32_e32 v99, v104
	v_add_f32_e32 v96, v144, v96
	v_add_f32_e32 v107, v96, v97
	v_mov_b32_e32 v96, v124
	v_mov_b32_e32 v97, v120
	v_pk_mul_f32 v[96:97], v[88:89], v[96:97]
	v_add_f32_e32 v86, 0, v86
	v_add_f32_e32 v96, v127, v96
	v_add_f32_e32 v96, v96, v97
	v_add_f32_e32 v97, v92, v93
	v_pk_mul_f32 v[92:93], v[90:91], v[236:237]
	v_pk_mul_f32 v[90:91], v[90:91], v[244:245]
	v_add_f32_e32 v92, 0, v92
	v_add_f32_e32 v90, 0, v90
	v_mov_b32_e32 v104, v109
	v_add_f32_e32 v92, v92, v93
	v_add_f32_e32 v90, v90, v91
	v_add_f32_e32 v91, v86, v87
	v_pk_mul_f32 v[86:87], v[88:89], v[104:105]
	v_mov_b32_e32 v98, v108
	v_add_f32_e32 v86, v92, v86
	v_mov_b32_e32 v120, v125
	v_pk_mul_f32 v[98:99], v[88:89], v[98:99]
	v_add_f32_e32 v92, v86, v87
	v_pk_mul_f32 v[86:87], v[88:89], v[120:121]
	v_add_f32_e32 v98, v126, v98
	v_add_f32_e32 v86, v90, v86
	v_mov_b32_e32 v112, v117
	v_add_f32_e32 v98, v98, v99
	v_add_f32_e32 v99, v86, v87
	v_pk_mul_f32 v[86:87], v[112:113], v[94:95]
	v_mul_f32_e32 v108, 0x3d800000, v96
	v_add_f32_e32 v86, v91, v86
	v_add_f32_e32 v94, v86, v87
	v_cvt_pk_bf16_f32 v86, v131, v138
	v_cvt_pk_bf16_f32 v87, v135, v129
	v_cvt_pk_bf16_f32 v88, v106, v102
	v_cvt_pk_bf16_f32 v89, v98, v92
	v_cvt_pk_bf16_f32 v90, v132, v134
	v_cvt_pk_bf16_f32 v91, v139, v133
	v_cvt_pk_bf16_f32 v92, v110, v107
	v_cvt_pk_bf16_f32 v93, v96, v99
	v_cvt_pk_bf16_f32 v102, v128, v130
	v_cvt_pk_bf16_f32 v103, v140, v136
	v_cvt_pk_bf16_f32 v104, v100, v101
	v_cvt_pk_bf16_f32 v105, v97, v94
	v_mul_f32_e32 v97, 0x3d800000, v132
	v_mul_f32_e32 v98, 0x3d800000, v134
	v_mul_f32_e32 v99, 0x3d800000, v99
	v_lshl_add_u64 v[94:95], v[216:217], 0, v[206:207]
	v_mul_f32_e32 v100, 0x3d800000, v139
	v_mul_f32_e32 v101, 0x3d800000, v133
	v_mul_f32_e32 v106, 0x3d800000, v110
	v_mul_f32_e32 v107, 0x3d800000, v107
	global_store_dwordx4 v[94:95], v[86:89], off
	v_cvt_pk_bf16_f32 v94, v97, v98
	v_cvt_pk_bf16_f32 v95, v100, v101
	v_cvt_pk_bf16_f32 v96, v106, v107
	v_cvt_pk_bf16_f32 v97, v108, v99
	v_lshl_add_u64 v[98:99], v[214:215], 0, v[206:207]
	global_store_dwordx4 v[98:99], v[94:97], off
	ds_read_b128 v[118:121], v218
	ds_read_b128 v[114:117], v218 offset:16
	ds_read_b128 v[138:141], v218 offset:32768
	ds_read_b128 v[134:137], v218 offset:32784
	ds_read_b128 v[130:133], v222
	ds_read_b128 v[126:129], v222 offset:16
	ds_read_b128 v[110:113], v218 offset:32
	ds_read_b128 v[106:109], v218 offset:48
	v_mfma_f32_16x16x32_bf16 v[66:69], v[86:89], v[18:21], v[66:69]
	v_lshl_add_u64 v[86:87], v[224:225], 0, v[190:191]
	v_lshl_add_u64 v[88:89], v[224:225], 0, v[192:193]
	v_lshl_add_u64 v[98:99], v[224:225], 0, v[196:197]
	v_mfma_f32_16x16x32_bf16 v[66:69], v[90:93], v[14:17], v[66:69]
	global_load_dwordx4 v[94:97], v[86:87], off
	global_load_dwordx4 v[90:93], v[88:89], off
	v_lshl_add_u64 v[86:87], v[224:225], 0, v[194:195]
	global_load_dwordx4 v[86:89], v[86:87], off
	s_nop 0
	global_load_dwordx4 v[98:101], v[98:99], off
	s_nop 0
	ds_read_b128 v[146:149], v218 offset:32816
	ds_read_b128 v[150:153], v218 offset:32800
	ds_read_b128 v[122:125], v222 offset:48
	ds_read_b128 v[142:145], v222 offset:32
	s_waitcnt vmcnt(6)
; __device__ __forceinline__ void unpack8(u32x4 w, float* f) { f[0] = bflo(w.x); f[1] = bfhi(w.x); f[2] = bflo(w.y); f[3] = bfhi(w.y); f[4] = bflo(w.z); f[5] = bfhi(w.z); f[6] = bflo(w.w); f[7] = bfhi(w.w); }
; __device__ __forceinline__ float fsig0(float x) { return __builtin_amdgcn_rcpf(1.0f + __expf(-x)); }
; #define MQ_LOAD(dst, mm) do { const int tk_ = row0 + 16 * (mm) + (lane & 15), s_ = tk_ & (SEQL - 1); \
;                 _Pragma("unroll") for (int j = 0; j < 4; ++j) dst[j] = (s_ - 3 + j >= 0) ? *(const u32x4*)(XM + (size_t)(tk_ - 3 + j) * 2048 + c0) : (u32x4){0u, 0u, 0u, 0u}; } while (0)
; __device__ void mqk_phase(const Params& p, unsigned char* smem) {
;     ...
;             for (int m = 0; m < 4; ++m) {
;                 const int tk = row0 + 16 * m + (lane & 15);
;                 u32x4 xnx[4];
;                 if (m < 3) MQ_LOAD(xnx, m + 1);
;                 float xmc[8], xcur[8];
; #pragma unroll
;                 for (int i = 0; i < 8; ++i) xmc[i] = cbv[i];
; #pragma unroll
;                 for (int j = 0; j < 4; ++j) { float xv[8]; unpack8(xraw[j], xv);
; #pragma unroll
;                     for (int i = 0; i < 8; ++i) { xmc[i] += cw[j][i] * xv[i]; if (j == 3) xcur[i] = xv[i]; } }
;                 if (m < 3) {
; #pragma unroll
;                     for (int j = 0; j < 4; ++j) xraw[j] = xnx[j]; }
; #pragma unroll
;                 for (int i = 0; i < 8; ++i) xmc[i] = xmc[i] * fsig0(xmc[i]);
;                 float qv[8], kv[8], vv[8];
; #pragma unroll
;                 for (int bb = 0; bb < 2; ++bb)
; #pragma unroll
;                     for (int jj = 0; jj < 4; ++jj) { float aq = 0.f, ak = 0.f, av = 0.f;
; #pragma unroll
;                         for (int ii = 0; ii < 4; ++ii) { aq += xmc[4 * bb + ii] * wqp[bb * 16 + ii * 4 + jj]; ak += xmc[4 * bb + ii] * wkp[bb * 16 + ii * 4 + jj]; av += xcur[4 * bb + ii] * wvp[bb * 16 + ii * 4 + jj]; }
;                         qv[4 * bb + jj] = aq; kv[4 * bb + jj] = ak; vv[4 * bb + jj] = av; }
	v_lshlrev_b32_e32 v226, 16, v82
	v_and_b32_e32 v227, 0xffff0000, v82
	v_mfma_f32_16x16x32_bf16 v[66:69], v[102:105], v[10:13], v[66:69]
	s_nop 0
	s_waitcnt lgkmcnt(11)
	v_mov_b32_e32 v154, v118
	s_nop 0
	s_waitcnt lgkmcnt(10)
	v_mov_b32_e32 v155, v114
	v_pk_mul_f32 v[154:155], v[154:155], v[226:227]
	v_mov_b32_e32 v114, v119
	v_add_f32_e32 v82, 0, v154
	v_pk_mul_f32 v[114:115], v[114:115], v[226:227]
	v_add_f32_e32 v156, v82, v155
	v_add_f32_e32 v82, 0, v114
	v_add_f32_e32 v157, v82, v115
	v_lshlrev_b32_e32 v114, 16, v78
	v_and_b32_e32 v115, 0xffff0000, v78
	v_pk_fma_f32 v[114:115], v[46:47], v[114:115], v[58:59]
	v_lshlrev_b32_e32 v118, 16, v74
	v_and_b32_e32 v119, 0xffff0000, v74
	v_pk_fma_f32 v[114:115], v[50:51], v[118:119], v[114:115]
	v_lshlrev_b32_e32 v118, 16, v70
	v_and_b32_e32 v119, 0xffff0000, v70
	v_pk_fma_f32 v[114:115], v[54:55], v[118:119], v[114:115]
	v_mov_b32_e32 v119, v116
	v_pk_fma_f32 v[114:115], v[42:43], v[226:227], v[114:115]
	v_mov_b32_e32 v118, v120
	v_mul_f32_e32 v70, 0xbfb8aa3b, v114
	v_exp_f32_e32 v70, v70
	v_mul_f32_e32 v74, 0xbfb8aa3b, v115
	v_exp_f32_e32 v74, v74
	v_pk_mul_f32 v[118:119], v[118:119], v[226:227]
	v_add_f32_e32 v70, 1.0, v70
	v_rcp_f32_e32 v154, v70
	v_add_f32_e32 v70, 1.0, v74
	v_rcp_f32_e32 v155, v70
	v_add_f32_e32 v70, 0, v118
	v_lshlrev_b32_e32 v82, 16, v83
	v_and_b32_e32 v83, 0xffff0000, v83
	v_pk_mul_f32 v[114:115], v[114:115], v[154:155]
	s_nop 0
	s_waitcnt lgkmcnt(9)
	v_mov_b32_e32 v154, v138
	s_nop 0
	s_waitcnt lgkmcnt(8)
	v_mov_b32_e32 v155, v134
	v_pk_mul_f32 v[154:155], v[114:115], v[154:155]
	v_mov_b32_e32 v134, v139
	v_add_f32_e32 v74, 0, v154
	v_add_f32_e32 v116, v74, v155
	s_nop 0
	s_waitcnt lgkmcnt(7)
	v_mov_b32_e32 v154, v130
	s_nop 0
	s_waitcnt lgkmcnt(6)
	v_mov_b32_e32 v155, v126
	v_pk_mul_f32 v[154:155], v[114:115], v[154:155]
	v_pk_mul_f32 v[134:135], v[114:115], v[134:135]
	v_add_f32_e32 v74, 0, v154
	v_mov_b32_e32 v126, v131
	v_add_f32_e32 v120, v74, v155
	v_add_f32_e32 v74, 0, v134
	v_pk_mul_f32 v[126:127], v[114:115], v[126:127]
	v_add_f32_e32 v134, v74, v135
	v_add_f32_e32 v74, 0, v126
	v_add_f32_e32 v135, v74, v127
	v_mov_b32_e32 v127, v128
	v_add_f32_e32 v128, v70, v119
	s_nop 0
	s_waitcnt lgkmcnt(5)
	v_mov_b32_e32 v118, v110
	s_nop 0
	s_waitcnt lgkmcnt(4)
	v_mov_b32_e32 v119, v106
	v_pk_mul_f32 v[118:119], v[118:119], v[82:83]
	v_mov_b32_e32 v106, v111
	v_add_f32_e32 v70, v156, v118
	v_pk_mul_f32 v[106:107], v[106:107], v[82:83]
	v_mov_b32_e32 v126, v132
	v_mov_b32_e32 v130, v140
	v_mov_b32_e32 v131, v136
	v_add_f32_e32 v132, v70, v119
	v_add_f32_e32 v70, v157, v106
	ds_read_b128 v[154:157], v218 offset:80
	ds_read_b128 v[158:161], v218 offset:64
	v_pk_mul_f32 v[130:131], v[114:115], v[130:131]
	v_pk_mul_f32 v[126:127], v[114:115], v[126:127]
	v_add_f32_e32 v78, 0, v130
	v_add_f32_e32 v74, 0, v126
	v_add_f32_e32 v126, v78, v131
	v_lshlrev_b32_e32 v78, 16, v79
	v_and_b32_e32 v79, 0xffff0000, v79
	v_add_f32_e32 v127, v74, v127
	v_pk_fma_f32 v[78:79], v[48:49], v[78:79], v[60:61]
	v_lshlrev_b32_e32 v74, 16, v75
	v_and_b32_e32 v75, 0xffff0000, v75
	v_add_f32_e32 v138, v70, v107
	v_pk_fma_f32 v[74:75], v[52:53], v[74:75], v[78:79]
	v_lshlrev_b32_e32 v70, 16, v71
	v_and_b32_e32 v71, 0xffff0000, v71
	v_pk_fma_f32 v[70:71], v[56:57], v[70:71], v[74:75]
	ds_read_b128 v[234:237], v218 offset:32848
	ds_read_b128 v[238:241], v218 offset:32832
	v_pk_fma_f32 v[70:71], v[44:45], v[82:83], v[70:71]
	ds_read_b128 v[242:245], v222 offset:80
	ds_read_b128 v[246:249], v222 offset:64
	v_mul_f32_e32 v74, 0xbfb8aa3b, v70
	v_exp_f32_e32 v75, v74
	v_mul_f32_e32 v74, 0xbfb8aa3b, v71
	v_exp_f32_e32 v79, v74
	v_mov_b32_e32 v74, v112
	v_add_f32_e32 v75, 1.0, v75
	v_rcp_f32_e32 v78, v75
	v_add_f32_e32 v75, 1.0, v79
	v_rcp_f32_e32 v79, v75
	v_mov_b32_e32 v75, v108
	v_pk_mul_f32 v[74:75], v[74:75], v[82:83]
	v_mov_b32_e32 v136, v141
	v_pk_mul_f32 v[70:71], v[70:71], v[78:79]
	s_nop 0
	s_waitcnt lgkmcnt(8)
	v_mov_b32_e32 v78, v150
	v_mov_b32_e32 v79, v146
	v_pk_mul_f32 v[78:79], v[70:71], v[78:79]
	v_mov_b32_e32 v146, v151
	v_add_f32_e32 v78, v116, v78
	v_add_f32_e32 v139, v78, v79
	s_nop 0
	s_waitcnt lgkmcnt(6)
	v_mov_b32_e32 v78, v142
	v_mov_b32_e32 v79, v122
	v_pk_mul_f32 v[78:79], v[70:71], v[78:79]
	v_mov_b32_e32 v122, v143
	v_add_f32_e32 v78, v120, v78
	v_add_f32_e32 v140, v78, v79
	v_pk_mul_f32 v[78:79], v[70:71], v[146:147]
	v_add_f32_e32 v74, v128, v74
	v_add_f32_e32 v78, v134, v78
	v_add_f32_e32 v134, v78, v79
	v_pk_mul_f32 v[78:79], v[70:71], v[122:123]
	v_mov_b32_e32 v128, v133
	v_add_f32_e32 v78, v135, v78
	v_add_f32_e32 v135, v78, v79
	v_mov_b32_e32 v78, v144
	v_mov_b32_e32 v79, v124
	v_pk_mul_f32 v[78:79], v[70:71], v[78:79]
	v_add_f32_e32 v144, v74, v75
	v_pk_mul_f32 v[74:75], v[114:115], v[136:137]
	v_add_f32_e32 v78, v127, v78
	v_add_f32_e32 v74, 0, v74
	v_add_f32_e32 v143, v78, v79
	v_add_f32_e32 v78, v74, v75
	v_pk_mul_f32 v[74:75], v[114:115], v[128:129]
	v_mov_b32_e32 v116, v121
	v_add_f32_e32 v74, 0, v74
	v_add_f32_e32 v79, v74, v75
	v_pk_mul_f32 v[74:75], v[116:117], v[226:227]
	ds_read_b128 v[114:117], v218 offset:112
	ds_read_b128 v[118:121], v218 offset:96
	v_mov_b32_e32 v106, v152
	v_mov_b32_e32 v107, v148
	v_pk_mul_f32 v[106:107], v[70:71], v[106:107]
	v_add_f32_e32 v74, 0, v74
	v_add_f32_e32 v106, v126, v106
	v_mov_b32_e32 v148, v153
	v_mov_b32_e32 v124, v145
	v_add_f32_e32 v142, v106, v107
	v_add_f32_e32 v106, v74, v75
	v_pk_mul_f32 v[74:75], v[70:71], v[148:149]
	v_pk_mul_f32 v[70:71], v[70:71], v[124:125]
	v_mov_b32_e32 v108, v113
	v_add_f32_e32 v70, v79, v70
	v_add_f32_e32 v136, v70, v71
	v_pk_mul_f32 v[70:71], v[108:109], v[82:83]
	v_add_f32_e32 v74, v78, v74
	v_add_f32_e32 v70, v106, v70
	ds_read_b128 v[106:109], v218 offset:32880
	ds_read_b128 v[110:113], v218 offset:32864
	ds_read_b128 v[122:125], v222 offset:112
	ds_read_b128 v[126:129], v222 offset:96
	v_add_f32_e32 v133, v74, v75
	v_add_f32_e32 v137, v70, v71
	v_lshlrev_b32_e32 v70, 16, v84
	v_and_b32_e32 v71, 0xffff0000, v84
	s_nop 0
	s_waitcnt lgkmcnt(10)
; __device__ __forceinline__ u32x4 pack8(const float* f) { u32x4 w; w.x = pk2(f[0], f[1]); w.y = pk2(f[2], f[3]); w.z = pk2(f[4], f[5]); w.w = pk2(f[6], f[7]); return w; }
; #define MFMA16(a, b, c) __builtin_amdgcn_mfma_f32_16x16x32_bf16((a), (b), (c), 0, 0, 0)
; __device__ __forceinline__ float fsig0(float x) { return __builtin_amdgcn_rcpf(1.0f + __expf(-x)); }
; __device__ void mqk_phase(const Params& p, unsigned char* smem) {
;     ...
;                 for (int i = 0; i < 8; ++i) xmc[i] = xmc[i] * fsig0(xmc[i]);
;                 float qv[8], kv[8], vv[8];
; #pragma unroll
;                 for (int bb = 0; bb < 2; ++bb)
; #pragma unroll
;                     for (int jj = 0; jj < 4; ++jj) { float aq = 0.f, ak = 0.f, av = 0.f;
; #pragma unroll
;                         for (int ii = 0; ii < 4; ++ii) { aq += xmc[4 * bb + ii] * wqp[bb * 16 + ii * 4 + jj]; ak += xmc[4 * bb + ii] * wkp[bb * 16 + ii * 4 + jj]; av += xcur[4 * bb + ii] * wvp[bb * 16 + ii * 4 + jj]; }
;                         qv[4 * bb + jj] = aq; kv[4 * bb + jj] = ak; vv[4 * bb + jj] = av; }
;                 const u32x4 qw = pack8(qv), kw = pack8(kv), vw = pack8(vv);
;                 acc[m] = MFMA16(as_frag(qw), bq, acc[m]); acc[m] = MFMA16(as_frag(kw), bk, acc[m]); acc[m] = MFMA16(as_frag(vw), bv, acc[m]);
; #pragma unroll
;                 for (int i = 0; i < 8; ++i) kv[i] *= 0.0625f;
;                 *(u32x4*)(Q + (size_t)tk * 2048 + c0) = qw; *(u32x4*)(KX + (size_t)tk * 2048 + c0) = pack8(kv);
;             }
	v_mov_b32_e32 v74, v158
	v_mov_b32_e32 v75, v154
	v_pk_mul_f32 v[74:75], v[74:75], v[70:71]
	v_mov_b32_e32 v154, v159
	v_add_f32_e32 v74, 0, v74
	v_add_f32_e32 v84, v74, v75
	v_pk_mul_f32 v[74:75], v[154:155], v[70:71]
	v_lshlrev_b32_e32 v78, 16, v76
	v_add_f32_e32 v74, 0, v74
	v_add_f32_e32 v141, v74, v75
	v_lshlrev_b32_e32 v74, 16, v80
	v_and_b32_e32 v75, 0xffff0000, v80
	v_pk_fma_f32 v[74:75], v[22:23], v[74:75], v[38:39]
	v_and_b32_e32 v79, 0xffff0000, v76
	v_pk_fma_f32 v[74:75], v[26:27], v[78:79], v[74:75]
	v_lshlrev_b32_e32 v78, 16, v72
	v_and_b32_e32 v79, 0xffff0000, v72
	v_pk_fma_f32 v[74:75], v[30:31], v[78:79], v[74:75]
	v_mov_b32_e32 v78, v160
	v_pk_fma_f32 v[74:75], v[34:35], v[70:71], v[74:75]
	v_mov_b32_e32 v79, v156
	v_mul_f32_e32 v72, 0xbfb8aa3b, v74
	v_exp_f32_e32 v72, v72
	v_mul_f32_e32 v76, 0xbfb8aa3b, v75
	v_exp_f32_e32 v76, v76
	s_nop 0
	s_waitcnt lgkmcnt(8)
	v_mov_b32_e32 v130, v240
	v_add_f32_e32 v72, 1.0, v72
	v_rcp_f32_e32 v82, v72
	v_add_f32_e32 v72, 1.0, v76
	v_rcp_f32_e32 v83, v72
	v_mov_b32_e32 v131, v236
	v_pk_mul_f32 v[78:79], v[78:79], v[70:71]
	v_lshlrev_b32_e32 v80, 16, v81
	v_pk_mul_f32 v[74:75], v[74:75], v[82:83]
	v_mov_b32_e32 v82, v238
	v_mov_b32_e32 v83, v234
	v_pk_mul_f32 v[82:83], v[74:75], v[82:83]
	v_mov_b32_e32 v234, v239
	v_add_f32_e32 v76, 0, v82
	v_add_f32_e32 v145, v76, v83
	s_nop 0
	s_waitcnt lgkmcnt(6)
	v_mov_b32_e32 v82, v246
	v_mov_b32_e32 v83, v242
	v_pk_mul_f32 v[82:83], v[74:75], v[82:83]
	v_mov_b32_e32 v242, v247
	v_add_f32_e32 v76, 0, v82
	v_add_f32_e32 v146, v76, v83
	v_pk_mul_f32 v[82:83], v[74:75], v[234:235]
	v_pk_mul_f32 v[130:131], v[74:75], v[130:131]
	v_add_f32_e32 v76, 0, v82
	v_add_f32_e32 v147, v76, v83
	v_pk_mul_f32 v[82:83], v[74:75], v[242:243]
	v_add_f32_e32 v72, 0, v78
	v_add_f32_e32 v76, 0, v82
	v_add_f32_e32 v148, v76, v83
	v_mov_b32_e32 v82, v248
	v_mov_b32_e32 v83, v244
	v_pk_mul_f32 v[82:83], v[74:75], v[82:83]
	v_add_f32_e32 v78, 0, v130
	v_add_f32_e32 v76, 0, v82
	v_add_f32_e32 v130, v78, v131
	v_add_f32_e32 v131, v76, v83
	v_add_f32_e32 v149, v72, v79
	v_lshlrev_b32_e32 v78, 16, v85
	v_and_b32_e32 v79, 0xffff0000, v85
	s_nop 0
	s_waitcnt lgkmcnt(4)
	v_mov_b32_e32 v82, v118
	v_mov_b32_e32 v83, v114
	v_pk_mul_f32 v[82:83], v[82:83], v[78:79]
	v_mov_b32_e32 v114, v119
	v_add_f32_e32 v72, v84, v82
	v_add_f32_e32 v84, v72, v83
	v_pk_mul_f32 v[82:83], v[114:115], v[78:79]
	v_and_b32_e32 v81, 0xffff0000, v81
	v_add_f32_e32 v72, v141, v82
	v_pk_fma_f32 v[80:81], v[24:25], v[80:81], v[40:41]
	v_lshlrev_b32_e32 v76, 16, v77
	v_and_b32_e32 v77, 0xffff0000, v77
	v_add_f32_e32 v85, v72, v83
	v_pk_fma_f32 v[76:77], v[28:29], v[76:77], v[80:81]
	v_lshlrev_b32_e32 v72, 16, v73
	v_and_b32_e32 v73, 0xffff0000, v73
	v_pk_fma_f32 v[72:73], v[32:33], v[72:73], v[76:77]
	v_mov_b32_e32 v236, v241
	v_pk_fma_f32 v[72:73], v[36:37], v[78:79], v[72:73]
	v_mov_b32_e32 v244, v249
	v_mul_f32_e32 v76, 0xbfb8aa3b, v72
	v_exp_f32_e32 v77, v76
	v_mul_f32_e32 v76, 0xbfb8aa3b, v73
	v_exp_f32_e32 v81, v76
	v_mov_b32_e32 v76, v120
	v_add_f32_e32 v77, 1.0, v77
	v_rcp_f32_e32 v80, v77
	v_add_f32_e32 v77, 1.0, v81
	v_rcp_f32_e32 v81, v77
	v_mov_b32_e32 v77, v116
	v_pk_mul_f32 v[76:77], v[76:77], v[78:79]
	v_mov_b32_e32 v156, v161
	v_pk_mul_f32 v[72:73], v[72:73], v[80:81]
	s_nop 0
	s_waitcnt lgkmcnt(2)
	v_mov_b32_e32 v80, v110
	v_mov_b32_e32 v81, v106
	v_pk_mul_f32 v[80:81], v[72:73], v[80:81]
	v_mov_b32_e32 v106, v111
	v_add_f32_e32 v80, v145, v80
	v_add_f32_e32 v110, v80, v81
	s_nop 0
	s_waitcnt lgkmcnt(0)
	v_mov_b32_e32 v80, v126
	v_mov_b32_e32 v81, v122
	v_pk_mul_f32 v[80:81], v[72:73], v[80:81]
	v_mov_b32_e32 v122, v127
	v_add_f32_e32 v80, v146, v80
	v_add_f32_e32 v114, v80, v81
	v_pk_mul_f32 v[80:81], v[72:73], v[106:107]
	v_add_f32_e32 v76, v149, v76
	v_add_f32_e32 v80, v147, v80
	v_add_f32_e32 v106, v80, v81
	v_pk_mul_f32 v[80:81], v[72:73], v[122:123]
	v_pk_mul_f32 v[70:71], v[156:157], v[70:71]
	v_add_f32_e32 v80, v148, v80
	v_add_f32_e32 v111, v80, v81
	v_mov_b32_e32 v80, v128
	v_mov_b32_e32 v81, v124
	v_pk_mul_f32 v[80:81], v[72:73], v[80:81]
	v_mov_b32_e32 v83, v108
	v_add_f32_e32 v80, v131, v80
	v_add_f32_e32 v80, v80, v81
	v_add_f32_e32 v81, v76, v77
	v_pk_mul_f32 v[76:77], v[74:75], v[236:237]
	v_pk_mul_f32 v[74:75], v[74:75], v[244:245]
	v_add_f32_e32 v76, 0, v76
	v_add_f32_e32 v74, 0, v74
	v_add_f32_e32 v70, 0, v70
	v_mov_b32_e32 v108, v113
	v_add_f32_e32 v76, v76, v77
	v_add_f32_e32 v74, v74, v75
	v_add_f32_e32 v75, v70, v71
	v_pk_mul_f32 v[70:71], v[72:73], v[108:109]
	v_mov_b32_e32 v82, v112
	v_add_f32_e32 v70, v76, v70
	v_mov_b32_e32 v124, v129
	v_pk_mul_f32 v[82:83], v[72:73], v[82:83]
	v_add_f32_e32 v76, v70, v71
	v_pk_mul_f32 v[70:71], v[72:73], v[124:125]
	v_add_f32_e32 v82, v130, v82
	v_add_f32_e32 v70, v74, v70
	v_mov_b32_e32 v116, v121
	v_add_f32_e32 v82, v82, v83
	v_add_f32_e32 v83, v70, v71
	v_pk_mul_f32 v[70:71], v[116:117], v[78:79]
	v_mul_f32_e32 v112, 0x3d800000, v80
	v_add_f32_e32 v70, v75, v70
	v_add_f32_e32 v78, v70, v71
	v_cvt_pk_bf16_f32 v70, v139, v134
	v_cvt_pk_bf16_f32 v71, v142, v133
	v_cvt_pk_bf16_f32 v72, v110, v106
	v_cvt_pk_bf16_f32 v73, v82, v76
	v_cvt_pk_bf16_f32 v74, v140, v135
	v_cvt_pk_bf16_f32 v75, v143, v136
	v_cvt_pk_bf16_f32 v76, v114, v111
	v_cvt_pk_bf16_f32 v77, v80, v83
	v_cvt_pk_bf16_f32 v106, v132, v138
	v_cvt_pk_bf16_f32 v107, v144, v137
	v_cvt_pk_bf16_f32 v108, v84, v85
	v_cvt_pk_bf16_f32 v109, v81, v78
	v_mul_f32_e32 v81, 0x3d800000, v140
	v_mul_f32_e32 v82, 0x3d800000, v135
	v_mul_f32_e32 v83, 0x3d800000, v83
	v_lshl_add_u64 v[78:79], v[216:217], 0, v[208:209]
	v_mul_f32_e32 v84, 0x3d800000, v143
	v_mul_f32_e32 v85, 0x3d800000, v136
	v_mul_f32_e32 v110, 0x3d800000, v114
	v_mul_f32_e32 v111, 0x3d800000, v111
	global_store_dwordx4 v[78:79], v[70:73], off
	v_cvt_pk_bf16_f32 v78, v81, v82
	v_cvt_pk_bf16_f32 v79, v84, v85
	v_cvt_pk_bf16_f32 v80, v110, v111
	v_cvt_pk_bf16_f32 v81, v112, v83
	v_lshl_add_u64 v[82:83], v[214:215], 0, v[208:209]
	global_store_dwordx4 v[82:83], v[78:81], off
	ds_read_b128 v[118:121], v218
	ds_read_b128 v[114:117], v218 offset:16
	ds_read_b128 v[138:141], v218 offset:32768
	ds_read_b128 v[134:137], v218 offset:32784
	ds_read_b128 v[130:133], v222
	ds_read_b128 v[126:129], v222 offset:16
	ds_read_b128 v[110:113], v218 offset:32
	ds_read_b128 v[102:105], v218 offset:48
	v_mfma_f32_16x16x32_bf16 v[62:65], v[70:73], v[18:21], v[62:65]
	v_lshl_add_u64 v[70:71], v[224:225], 0, v[198:199]
	v_lshl_add_u64 v[72:73], v[224:225], 0, v[200:201]
	v_lshl_add_u64 v[82:83], v[224:225], 0, v[204:205]
	v_mfma_f32_16x16x32_bf16 v[62:65], v[74:77], v[14:17], v[62:65]
	global_load_dwordx4 v[78:81], v[70:71], off
	global_load_dwordx4 v[74:77], v[72:73], off
	v_lshl_add_u64 v[70:71], v[224:225], 0, v[202:203]
	global_load_dwordx4 v[70:73], v[70:71], off
	s_nop 0
	global_load_dwordx4 v[82:85], v[82:83], off
	s_nop 0
	ds_read_b128 v[146:149], v218 offset:32816
	ds_read_b128 v[150:153], v218 offset:32800
	ds_read_b128 v[122:125], v222 offset:48
	ds_read_b128 v[142:145], v222 offset:32
	s_waitcnt vmcnt(6)
; __device__ __forceinline__ void unpack8(u32x4 w, float* f) { f[0] = bflo(w.x); f[1] = bfhi(w.x); f[2] = bflo(w.y); f[3] = bfhi(w.y); f[4] = bflo(w.z); f[5] = bfhi(w.z); f[6] = bflo(w.w); f[7] = bfhi(w.w); }
; __device__ __forceinline__ u32x4 pack8(const float* f) { u32x4 w; w.x = pk2(f[0], f[1]); w.y = pk2(f[2], f[3]); w.z = pk2(f[4], f[5]); w.w = pk2(f[6], f[7]); return w; }
; #define MFMA16(a, b, c) __builtin_amdgcn_mfma_f32_16x16x32_bf16((a), (b), (c), 0, 0, 0)
; __device__ __forceinline__ float fsig0(float x) { return __builtin_amdgcn_rcpf(1.0f + __expf(-x)); }
; __device__ void mqk_phase(const Params& p, unsigned char* smem) {
;     ...
;                 for (int j = 0; j < 4; ++j) { float xv[8]; unpack8(xraw[j], xv);
; #pragma unroll
;                     for (int i = 0; i < 8; ++i) { xmc[i] += cw[j][i] * xv[i]; if (j == 3) xcur[i] = xv[i]; } }
;                 if (m < 3) {
; #pragma unroll
;                     for (int j = 0; j < 4; ++j) xraw[j] = xnx[j]; }
; #pragma unroll
;                 for (int i = 0; i < 8; ++i) xmc[i] = xmc[i] * fsig0(xmc[i]);
;                 float qv[8], kv[8], vv[8];
; #pragma unroll
;                 for (int bb = 0; bb < 2; ++bb)
; #pragma unroll
;                     for (int jj = 0; jj < 4; ++jj) { float aq = 0.f, ak = 0.f, av = 0.f;
; #pragma unroll
;                         for (int ii = 0; ii < 4; ++ii) { aq += xmc[4 * bb + ii] * wqp[bb * 16 + ii * 4 + jj]; ak += xmc[4 * bb + ii] * wkp[bb * 16 + ii * 4 + jj]; av += xcur[4 * bb + ii] * wvp[bb * 16 + ii * 4 + jj]; }
;                         qv[4 * bb + jj] = aq; kv[4 * bb + jj] = ak; vv[4 * bb + jj] = av; }
;                 const u32x4 qw = pack8(qv), kw = pack8(kv), vw = pack8(vv);
;                 acc[m] = MFMA16(as_frag(qw), bq, acc[m]); acc[m] = MFMA16(as_frag(kw), bk, acc[m]); acc[m] = MFMA16(as_frag(vw), bv, acc[m]);
	v_lshlrev_b32_e32 v224, 16, v98
	v_and_b32_e32 v225, 0xffff0000, v98
	v_mfma_f32_16x16x32_bf16 v[62:65], v[106:109], v[10:13], v[62:65]
	s_nop 0
	s_waitcnt lgkmcnt(11)
	v_mov_b32_e32 v154, v118
	s_nop 0
	s_waitcnt lgkmcnt(10)
	v_mov_b32_e32 v155, v114
	v_pk_mul_f32 v[154:155], v[154:155], v[224:225]
	v_mov_b32_e32 v114, v119
	v_add_f32_e32 v98, 0, v154
	v_pk_mul_f32 v[114:115], v[114:115], v[224:225]
	v_add_f32_e32 v156, v98, v155
	v_add_f32_e32 v98, 0, v114
	v_add_f32_e32 v157, v98, v115
	v_lshlrev_b32_e32 v114, 16, v94
	v_and_b32_e32 v115, 0xffff0000, v94
	v_pk_fma_f32 v[114:115], v[46:47], v[114:115], v[58:59]
	v_lshlrev_b32_e32 v118, 16, v90
	v_and_b32_e32 v119, 0xffff0000, v90
	v_pk_fma_f32 v[114:115], v[50:51], v[118:119], v[114:115]
	v_lshlrev_b32_e32 v118, 16, v86
	v_and_b32_e32 v119, 0xffff0000, v86
	v_pk_fma_f32 v[114:115], v[54:55], v[118:119], v[114:115]
	v_mov_b32_e32 v119, v116
	v_pk_fma_f32 v[114:115], v[42:43], v[224:225], v[114:115]
	v_mov_b32_e32 v118, v120
	v_mul_f32_e32 v86, 0xbfb8aa3b, v114
	v_exp_f32_e32 v86, v86
	v_mul_f32_e32 v90, 0xbfb8aa3b, v115
	v_exp_f32_e32 v90, v90
	v_pk_mul_f32 v[118:119], v[118:119], v[224:225]
	v_add_f32_e32 v86, 1.0, v86
	v_rcp_f32_e32 v154, v86
	v_add_f32_e32 v86, 1.0, v90
	v_rcp_f32_e32 v155, v86
	v_add_f32_e32 v86, 0, v118
	v_lshlrev_b32_e32 v98, 16, v99
	v_and_b32_e32 v99, 0xffff0000, v99
	v_pk_mul_f32 v[114:115], v[114:115], v[154:155]
	s_nop 0
	s_waitcnt lgkmcnt(9)
	v_mov_b32_e32 v154, v138
	s_nop 0
	s_waitcnt lgkmcnt(8)
	v_mov_b32_e32 v155, v134
	v_pk_mul_f32 v[154:155], v[114:115], v[154:155]
	v_mov_b32_e32 v134, v139
	v_add_f32_e32 v90, 0, v154
	v_add_f32_e32 v116, v90, v155
	s_nop 0
	s_waitcnt lgkmcnt(7)
	v_mov_b32_e32 v154, v130
	s_nop 0
	s_waitcnt lgkmcnt(6)
	v_mov_b32_e32 v155, v126
	v_pk_mul_f32 v[154:155], v[114:115], v[154:155]
	v_pk_mul_f32 v[134:135], v[114:115], v[134:135]
	v_add_f32_e32 v90, 0, v154
	v_mov_b32_e32 v126, v131
	v_add_f32_e32 v120, v90, v155
	v_add_f32_e32 v90, 0, v134
	v_pk_mul_f32 v[126:127], v[114:115], v[126:127]
	v_add_f32_e32 v134, v90, v135
	v_add_f32_e32 v90, 0, v126
	v_add_f32_e32 v135, v90, v127
	v_mov_b32_e32 v127, v128
	v_add_f32_e32 v128, v86, v119
	s_nop 0
	s_waitcnt lgkmcnt(5)
	v_mov_b32_e32 v118, v110
	s_nop 0
	s_waitcnt lgkmcnt(4)
	v_mov_b32_e32 v119, v102
	v_pk_mul_f32 v[118:119], v[118:119], v[98:99]
	v_mov_b32_e32 v102, v111
	v_add_f32_e32 v86, v156, v118
	v_pk_mul_f32 v[102:103], v[102:103], v[98:99]
	v_mov_b32_e32 v126, v132
	v_mov_b32_e32 v130, v140
	v_mov_b32_e32 v131, v136
	v_add_f32_e32 v132, v86, v119
	v_add_f32_e32 v86, v157, v102
	ds_read_b128 v[154:157], v218 offset:80
	ds_read_b128 v[158:161], v218 offset:64
	v_pk_mul_f32 v[130:131], v[114:115], v[130:131]
	v_pk_mul_f32 v[126:127], v[114:115], v[126:127]
	v_add_f32_e32 v94, 0, v130
	v_add_f32_e32 v90, 0, v126
	v_add_f32_e32 v126, v94, v131
	v_lshlrev_b32_e32 v94, 16, v95
	v_and_b32_e32 v95, 0xffff0000, v95
	v_add_f32_e32 v127, v90, v127
	v_pk_fma_f32 v[94:95], v[48:49], v[94:95], v[60:61]
	v_lshlrev_b32_e32 v90, 16, v91
	v_and_b32_e32 v91, 0xffff0000, v91
	v_add_f32_e32 v138, v86, v103
	v_pk_fma_f32 v[90:91], v[52:53], v[90:91], v[94:95]
	v_lshlrev_b32_e32 v86, 16, v87
	v_and_b32_e32 v87, 0xffff0000, v87
	v_pk_fma_f32 v[86:87], v[56:57], v[86:87], v[90:91]
	ds_read_b128 v[234:237], v218 offset:32848
	ds_read_b128 v[238:241], v218 offset:32832
	v_pk_fma_f32 v[86:87], v[44:45], v[98:99], v[86:87]
	ds_read_b128 v[242:245], v222 offset:80
	ds_read_b128 v[246:249], v222 offset:64
	v_mul_f32_e32 v90, 0xbfb8aa3b, v86
	v_exp_f32_e32 v91, v90
	v_mul_f32_e32 v90, 0xbfb8aa3b, v87
	v_exp_f32_e32 v95, v90
	v_mov_b32_e32 v90, v112
	v_add_f32_e32 v91, 1.0, v91
	v_rcp_f32_e32 v94, v91
	v_add_f32_e32 v91, 1.0, v95
	v_rcp_f32_e32 v95, v91
	v_mov_b32_e32 v91, v104
	v_pk_mul_f32 v[90:91], v[90:91], v[98:99]
	v_mov_b32_e32 v136, v141
	v_pk_mul_f32 v[86:87], v[86:87], v[94:95]
	s_nop 0
	s_waitcnt lgkmcnt(8)
	v_mov_b32_e32 v94, v150
	v_mov_b32_e32 v95, v146
	v_pk_mul_f32 v[94:95], v[86:87], v[94:95]
	v_mov_b32_e32 v146, v151
	v_add_f32_e32 v94, v116, v94
	v_add_f32_e32 v139, v94, v95
	s_nop 0
	s_waitcnt lgkmcnt(6)
	v_mov_b32_e32 v94, v142
	v_mov_b32_e32 v95, v122
	v_pk_mul_f32 v[94:95], v[86:87], v[94:95]
	v_mov_b32_e32 v122, v143
	v_add_f32_e32 v94, v120, v94
	v_add_f32_e32 v140, v94, v95
	v_pk_mul_f32 v[94:95], v[86:87], v[146:147]
	v_add_f32_e32 v90, v128, v90
	v_add_f32_e32 v94, v134, v94
	v_add_f32_e32 v134, v94, v95
	v_pk_mul_f32 v[94:95], v[86:87], v[122:123]
	v_mov_b32_e32 v128, v133
	v_add_f32_e32 v94, v135, v94
	v_add_f32_e32 v135, v94, v95
	v_mov_b32_e32 v94, v144
	v_mov_b32_e32 v95, v124
	v_pk_mul_f32 v[94:95], v[86:87], v[94:95]
	v_add_f32_e32 v144, v90, v91
	v_pk_mul_f32 v[90:91], v[114:115], v[136:137]
	v_add_f32_e32 v94, v127, v94
	v_add_f32_e32 v90, 0, v90
	v_add_f32_e32 v143, v94, v95
	v_add_f32_e32 v94, v90, v91
	v_pk_mul_f32 v[90:91], v[114:115], v[128:129]
	v_mov_b32_e32 v116, v121
	v_add_f32_e32 v90, 0, v90
	v_add_f32_e32 v95, v90, v91
	v_pk_mul_f32 v[90:91], v[116:117], v[224:225]
	ds_read_b128 v[114:117], v218 offset:112
	ds_read_b128 v[118:121], v218 offset:96
	v_mov_b32_e32 v102, v152
	v_mov_b32_e32 v103, v148
	v_pk_mul_f32 v[102:103], v[86:87], v[102:103]
	v_add_f32_e32 v90, 0, v90
	v_add_f32_e32 v102, v126, v102
	v_mov_b32_e32 v148, v153
	v_mov_b32_e32 v124, v145
	v_add_f32_e32 v142, v102, v103
	v_add_f32_e32 v102, v90, v91
	v_pk_mul_f32 v[90:91], v[86:87], v[148:149]
	v_pk_mul_f32 v[86:87], v[86:87], v[124:125]
	v_mov_b32_e32 v104, v113
	v_add_f32_e32 v86, v95, v86
	v_add_f32_e32 v136, v86, v87
	v_pk_mul_f32 v[86:87], v[104:105], v[98:99]
	v_add_f32_e32 v90, v94, v90
	v_add_f32_e32 v86, v102, v86
	ds_read_b128 v[102:105], v218 offset:32880
	ds_read_b128 v[110:113], v218 offset:32864
	ds_read_b128 v[122:125], v222 offset:112
	ds_read_b128 v[126:129], v222 offset:96
	v_add_f32_e32 v133, v90, v91
	v_add_f32_e32 v137, v86, v87
	v_lshlrev_b32_e32 v86, 16, v100
	v_and_b32_e32 v87, 0xffff0000, v100
	s_nop 0
	s_waitcnt lgkmcnt(10)
; __device__ __forceinline__ u32x4 pack8(const float* f) { u32x4 w; w.x = pk2(f[0], f[1]); w.y = pk2(f[2], f[3]); w.z = pk2(f[4], f[5]); w.w = pk2(f[6], f[7]); return w; }
; #define MFMA16(a, b, c) __builtin_amdgcn_mfma_f32_16x16x32_bf16((a), (b), (c), 0, 0, 0)
; __device__ __forceinline__ float fsig0(float x) { return __builtin_amdgcn_rcpf(1.0f + __expf(-x)); }
; __device__ void mqk_phase(const Params& p, unsigned char* smem) {
;     ...
;                 for (int i = 0; i < 8; ++i) xmc[i] = xmc[i] * fsig0(xmc[i]);
;                 float qv[8], kv[8], vv[8];
; #pragma unroll
;                 for (int bb = 0; bb < 2; ++bb)
; #pragma unroll
;                     for (int jj = 0; jj < 4; ++jj) { float aq = 0.f, ak = 0.f, av = 0.f;
; #pragma unroll
;                         for (int ii = 0; ii < 4; ++ii) { aq += xmc[4 * bb + ii] * wqp[bb * 16 + ii * 4 + jj]; ak += xmc[4 * bb + ii] * wkp[bb * 16 + ii * 4 + jj]; av += xcur[4 * bb + ii] * wvp[bb * 16 + ii * 4 + jj]; }
;                         qv[4 * bb + jj] = aq; kv[4 * bb + jj] = ak; vv[4 * bb + jj] = av; }
;                 const u32x4 qw = pack8(qv), kw = pack8(kv), vw = pack8(vv);
;                 acc[m] = MFMA16(as_frag(qw), bq, acc[m]); acc[m] = MFMA16(as_frag(kw), bk, acc[m]); acc[m] = MFMA16(as_frag(vw), bv, acc[m]);
; #pragma unroll
;                 for (int i = 0; i < 8; ++i) kv[i] *= 0.0625f;
;                 *(u32x4*)(Q + (size_t)tk * 2048 + c0) = qw; *(u32x4*)(KX + (size_t)tk * 2048 + c0) = pack8(kv);
;             }
	v_mov_b32_e32 v90, v158
	v_mov_b32_e32 v91, v154
	v_pk_mul_f32 v[90:91], v[90:91], v[86:87]
	v_mov_b32_e32 v154, v159
	v_add_f32_e32 v90, 0, v90
	v_add_f32_e32 v100, v90, v91
	v_pk_mul_f32 v[90:91], v[154:155], v[86:87]
	v_lshlrev_b32_e32 v94, 16, v92
	v_add_f32_e32 v90, 0, v90
	v_add_f32_e32 v141, v90, v91
	v_lshlrev_b32_e32 v90, 16, v96
	v_and_b32_e32 v91, 0xffff0000, v96
	v_pk_fma_f32 v[90:91], v[22:23], v[90:91], v[38:39]
	v_and_b32_e32 v95, 0xffff0000, v92
	v_pk_fma_f32 v[90:91], v[26:27], v[94:95], v[90:91]
	v_lshlrev_b32_e32 v94, 16, v88
	v_and_b32_e32 v95, 0xffff0000, v88
	v_pk_fma_f32 v[90:91], v[30:31], v[94:95], v[90:91]
	v_mov_b32_e32 v94, v160
	v_pk_fma_f32 v[90:91], v[34:35], v[86:87], v[90:91]
	v_mov_b32_e32 v95, v156
	v_mul_f32_e32 v88, 0xbfb8aa3b, v90
	v_exp_f32_e32 v88, v88
	v_mul_f32_e32 v92, 0xbfb8aa3b, v91
	v_exp_f32_e32 v92, v92
	s_nop 0
	s_waitcnt lgkmcnt(8)
	v_mov_b32_e32 v130, v240
	v_add_f32_e32 v88, 1.0, v88
	v_rcp_f32_e32 v98, v88
	v_add_f32_e32 v88, 1.0, v92
	v_rcp_f32_e32 v99, v88
	v_mov_b32_e32 v131, v236
	v_pk_mul_f32 v[94:95], v[94:95], v[86:87]
	v_lshlrev_b32_e32 v96, 16, v97
	v_pk_mul_f32 v[90:91], v[90:91], v[98:99]
	v_mov_b32_e32 v98, v238
	v_mov_b32_e32 v99, v234
	v_pk_mul_f32 v[98:99], v[90:91], v[98:99]
	v_mov_b32_e32 v234, v239
	v_add_f32_e32 v92, 0, v98
	v_add_f32_e32 v145, v92, v99
	s_nop 0
	s_waitcnt lgkmcnt(6)
	v_mov_b32_e32 v98, v246
	v_mov_b32_e32 v99, v242
	v_pk_mul_f32 v[98:99], v[90:91], v[98:99]
	v_mov_b32_e32 v242, v247
	v_add_f32_e32 v92, 0, v98
	v_add_f32_e32 v146, v92, v99
	v_pk_mul_f32 v[98:99], v[90:91], v[234:235]
	v_pk_mul_f32 v[130:131], v[90:91], v[130:131]
	v_add_f32_e32 v92, 0, v98
	v_add_f32_e32 v147, v92, v99
	v_pk_mul_f32 v[98:99], v[90:91], v[242:243]
	v_add_f32_e32 v88, 0, v94
	v_add_f32_e32 v92, 0, v98
	v_add_f32_e32 v148, v92, v99
	v_mov_b32_e32 v98, v248
	v_mov_b32_e32 v99, v244
	v_pk_mul_f32 v[98:99], v[90:91], v[98:99]
	v_add_f32_e32 v94, 0, v130
	v_add_f32_e32 v92, 0, v98
	v_add_f32_e32 v130, v94, v131
	v_add_f32_e32 v131, v92, v99
	v_add_f32_e32 v149, v88, v95
	v_lshlrev_b32_e32 v94, 16, v101
	v_and_b32_e32 v95, 0xffff0000, v101
	s_nop 0
	s_waitcnt lgkmcnt(4)
	v_mov_b32_e32 v98, v118
	v_mov_b32_e32 v99, v114
	v_pk_mul_f32 v[98:99], v[98:99], v[94:95]
	v_mov_b32_e32 v114, v119
	v_add_f32_e32 v88, v100, v98
	v_add_f32_e32 v100, v88, v99
	v_pk_mul_f32 v[98:99], v[114:115], v[94:95]
	v_and_b32_e32 v97, 0xffff0000, v97
	v_add_f32_e32 v88, v141, v98
	v_pk_fma_f32 v[96:97], v[24:25], v[96:97], v[40:41]
	v_lshlrev_b32_e32 v92, 16, v93
	v_and_b32_e32 v93, 0xffff0000, v93
	v_add_f32_e32 v101, v88, v99
	v_pk_fma_f32 v[92:93], v[28:29], v[92:93], v[96:97]
	v_lshlrev_b32_e32 v88, 16, v89
	v_and_b32_e32 v89, 0xffff0000, v89
	v_pk_fma_f32 v[88:89], v[32:33], v[88:89], v[92:93]
	v_mov_b32_e32 v236, v241
	v_pk_fma_f32 v[88:89], v[36:37], v[94:95], v[88:89]
	v_mov_b32_e32 v244, v249
	v_mul_f32_e32 v92, 0xbfb8aa3b, v88
	v_exp_f32_e32 v93, v92
	v_mul_f32_e32 v92, 0xbfb8aa3b, v89
	v_exp_f32_e32 v97, v92
	v_mov_b32_e32 v92, v120
	v_add_f32_e32 v93, 1.0, v93
	v_rcp_f32_e32 v96, v93
	v_add_f32_e32 v93, 1.0, v97
	v_rcp_f32_e32 v97, v93
	v_mov_b32_e32 v93, v116
	v_pk_mul_f32 v[92:93], v[92:93], v[94:95]
	v_mov_b32_e32 v156, v161
	v_pk_mul_f32 v[88:89], v[88:89], v[96:97]
	s_nop 0
	s_waitcnt lgkmcnt(2)
	v_mov_b32_e32 v96, v110
	v_mov_b32_e32 v97, v102
	v_pk_mul_f32 v[96:97], v[88:89], v[96:97]
	v_mov_b32_e32 v102, v111
	v_add_f32_e32 v96, v145, v96
	v_add_f32_e32 v110, v96, v97
	s_nop 0
	s_waitcnt lgkmcnt(0)
	v_mov_b32_e32 v96, v126
	v_mov_b32_e32 v97, v122
	v_pk_mul_f32 v[96:97], v[88:89], v[96:97]
	v_mov_b32_e32 v122, v127
	v_add_f32_e32 v96, v146, v96
	v_add_f32_e32 v114, v96, v97
	v_pk_mul_f32 v[96:97], v[88:89], v[102:103]
	v_add_f32_e32 v92, v149, v92
	v_add_f32_e32 v96, v147, v96
	v_add_f32_e32 v102, v96, v97
	v_pk_mul_f32 v[96:97], v[88:89], v[122:123]
	v_pk_mul_f32 v[86:87], v[156:157], v[86:87]
	v_add_f32_e32 v96, v148, v96
	v_add_f32_e32 v111, v96, v97
	v_mov_b32_e32 v96, v128
	v_mov_b32_e32 v97, v124
	v_pk_mul_f32 v[96:97], v[88:89], v[96:97]
	v_mov_b32_e32 v99, v104
	v_add_f32_e32 v96, v131, v96
	v_add_f32_e32 v96, v96, v97
	v_add_f32_e32 v97, v92, v93
	v_pk_mul_f32 v[92:93], v[90:91], v[236:237]
	v_pk_mul_f32 v[90:91], v[90:91], v[244:245]
	v_add_f32_e32 v92, 0, v92
	v_add_f32_e32 v90, 0, v90
	v_add_f32_e32 v86, 0, v86
	v_mov_b32_e32 v104, v113
	v_add_f32_e32 v92, v92, v93
	v_add_f32_e32 v90, v90, v91
	v_add_f32_e32 v91, v86, v87
	v_pk_mul_f32 v[86:87], v[88:89], v[104:105]
	v_mov_b32_e32 v98, v112
	v_add_f32_e32 v86, v92, v86
	v_mov_b32_e32 v124, v129
	v_pk_mul_f32 v[98:99], v[88:89], v[98:99]
	v_add_f32_e32 v92, v86, v87
	v_pk_mul_f32 v[86:87], v[88:89], v[124:125]
	v_add_f32_e32 v98, v130, v98
	v_add_f32_e32 v86, v90, v86
	v_mov_b32_e32 v116, v121
	v_add_f32_e32 v98, v98, v99
	v_add_f32_e32 v99, v86, v87
	v_pk_mul_f32 v[86:87], v[116:117], v[94:95]
	v_mul_f32_e32 v112, 0x3d800000, v96
	v_add_f32_e32 v86, v91, v86
	v_add_f32_e32 v94, v86, v87
	v_cvt_pk_bf16_f32 v86, v139, v134
	v_cvt_pk_bf16_f32 v87, v142, v133
	v_cvt_pk_bf16_f32 v88, v110, v102
	v_cvt_pk_bf16_f32 v89, v98, v92
	v_cvt_pk_bf16_f32 v90, v140, v135
	v_cvt_pk_bf16_f32 v91, v143, v136
	v_cvt_pk_bf16_f32 v92, v114, v111
	v_cvt_pk_bf16_f32 v93, v96, v99
	v_cvt_pk_bf16_f32 v102, v132, v138
	v_cvt_pk_bf16_f32 v103, v144, v137
	v_cvt_pk_bf16_f32 v104, v100, v101
	v_cvt_pk_bf16_f32 v105, v97, v94
	v_mul_f32_e32 v97, 0x3d800000, v140
	v_mul_f32_e32 v98, 0x3d800000, v135
	v_mul_f32_e32 v99, 0x3d800000, v99
	v_lshl_add_u64 v[94:95], v[216:217], 0, v[210:211]
	v_mul_f32_e32 v100, 0x3d800000, v143
	v_mul_f32_e32 v101, 0x3d800000, v136
	v_mul_f32_e32 v110, 0x3d800000, v114
	v_mul_f32_e32 v111, 0x3d800000, v111
	global_store_dwordx4 v[94:95], v[86:89], off
	v_cvt_pk_bf16_f32 v94, v97, v98
	v_cvt_pk_bf16_f32 v95, v100, v101
	v_cvt_pk_bf16_f32 v96, v110, v111
	v_cvt_pk_bf16_f32 v97, v112, v99
	v_lshl_add_u64 v[98:99], v[214:215], 0, v[210:211]
	global_store_dwordx4 v[98:99], v[94:97], off
	ds_read_b128 v[98:101], v218
	s_nop 0
	ds_read_b128 v[94:97], v218 offset:16
	ds_read_b128 v[130:133], v218 offset:32768
	ds_read_b128 v[126:129], v218 offset:32784
	ds_read_b128 v[122:125], v222
	ds_read_b128 v[118:121], v222 offset:16
	v_mfma_f32_16x16x32_bf16 v[2:5], v[86:89], v[18:21], v[2:5]
	s_waitcnt vmcnt(2)
; __device__ __forceinline__ void unpack8(u32x4 w, float* f) { f[0] = bflo(w.x); f[1] = bfhi(w.x); f[2] = bflo(w.y); f[3] = bfhi(w.y); f[4] = bflo(w.z); f[5] = bfhi(w.z); f[6] = bflo(w.w); f[7] = bfhi(w.w); }
; __device__ __forceinline__ u32x4 pack8(const float* f) { u32x4 w; w.x = pk2(f[0], f[1]); w.y = pk2(f[2], f[3]); w.z = pk2(f[4], f[5]); w.w = pk2(f[6], f[7]); return w; }
; #define MFMA16(a, b, c) __builtin_amdgcn_mfma_f32_16x16x32_bf16((a), (b), (c), 0, 0, 0)
; __device__ __forceinline__ float fsig0(float x) { return __builtin_amdgcn_rcpf(1.0f + __expf(-x)); }
; __device__ void mqk_phase(const Params& p, unsigned char* smem) {
;     ...
;                 for (int j = 0; j < 4; ++j) { float xv[8]; unpack8(xraw[j], xv);
; #pragma unroll
;                     for (int i = 0; i < 8; ++i) { xmc[i] += cw[j][i] * xv[i]; if (j == 3) xcur[i] = xv[i]; } }
;                 if (m < 3) {
; #pragma unroll
;                     for (int j = 0; j < 4; ++j) xraw[j] = xnx[j]; }
; #pragma unroll
;                 for (int i = 0; i < 8; ++i) xmc[i] = xmc[i] * fsig0(xmc[i]);
;                 float qv[8], kv[8], vv[8];
; #pragma unroll
;                 for (int bb = 0; bb < 2; ++bb)
; #pragma unroll
;                     for (int jj = 0; jj < 4; ++jj) { float aq = 0.f, ak = 0.f, av = 0.f;
; #pragma unroll
;                         for (int ii = 0; ii < 4; ++ii) { aq += xmc[4 * bb + ii] * wqp[bb * 16 + ii * 4 + jj]; ak += xmc[4 * bb + ii] * wkp[bb * 16 + ii * 4 + jj]; av += xcur[4 * bb + ii] * wvp[bb * 16 + ii * 4 + jj]; }
;                         qv[4 * bb + jj] = aq; kv[4 * bb + jj] = ak; vv[4 * bb + jj] = av; }
;                 const u32x4 qw = pack8(qv), kw = pack8(kv), vw = pack8(vv);
;                 acc[m] = MFMA16(as_frag(qw), bq, acc[m]); acc[m] = MFMA16(as_frag(kw), bk, acc[m]); acc[m] = MFMA16(as_frag(vw), bv, acc[m]);
	v_lshlrev_b32_e32 v134, 16, v82
	v_and_b32_e32 v135, 0xffff0000, v82
	s_nop 0
	s_waitcnt lgkmcnt(5)
	v_mov_b32_e32 v136, v98
	v_mfma_f32_16x16x32_bf16 v[2:5], v[90:93], v[14:17], v[2:5]
	ds_read_b128 v[90:93], v218 offset:32
	ds_read_b128 v[86:89], v218 offset:48
	s_nop 0
	s_waitcnt lgkmcnt(6)
	v_mov_b32_e32 v137, v94
	v_pk_mul_f32 v[136:137], v[136:137], v[134:135]
	v_mfma_f32_16x16x32_bf16 v[2:5], v[102:105], v[10:13], v[2:5]
	ds_read_b128 v[110:113], v218 offset:32816
	ds_read_b128 v[114:117], v218 offset:32800
	ds_read_b128 v[102:105], v222 offset:48
	ds_read_b128 v[106:109], v222 offset:32
	v_mov_b32_e32 v94, v99
	v_add_f32_e32 v82, 0, v136
	v_pk_mul_f32 v[94:95], v[94:95], v[134:135]
	v_add_f32_e32 v98, v82, v137
	v_add_f32_e32 v82, 0, v94
	v_add_f32_e32 v99, v82, v95
	v_lshlrev_b32_e32 v94, 16, v78
	v_and_b32_e32 v95, 0xffff0000, v78
	v_pk_fma_f32 v[46:47], v[46:47], v[94:95], v[58:59]
	v_lshlrev_b32_e32 v58, 16, v74
	v_and_b32_e32 v59, 0xffff0000, v74
	v_pk_fma_f32 v[46:47], v[50:51], v[58:59], v[46:47]
	v_lshlrev_b32_e32 v50, 16, v70
	v_and_b32_e32 v51, 0xffff0000, v70
	v_pk_fma_f32 v[46:47], v[54:55], v[50:51], v[46:47]
	v_lshlrev_b32_e32 v82, 16, v83
	v_pk_fma_f32 v[42:43], v[42:43], v[134:135], v[46:47]
	v_and_b32_e32 v83, 0xffff0000, v83
	v_mul_f32_e32 v46, 0xbfb8aa3b, v42
	v_exp_f32_e32 v47, v46
	v_mul_f32_e32 v46, 0xbfb8aa3b, v43
	v_exp_f32_e32 v51, v46
	v_mov_b32_e32 v46, v100
	v_add_f32_e32 v47, 1.0, v47
	v_rcp_f32_e32 v50, v47
	v_add_f32_e32 v47, 1.0, v51
	v_rcp_f32_e32 v51, v47
	v_mov_b32_e32 v47, v96
	v_pk_mul_f32 v[46:47], v[46:47], v[134:135]
	v_pk_mul_f32 v[94:95], v[42:43], v[50:51]
	s_nop 0
	s_waitcnt lgkmcnt(9)
	v_mov_b32_e32 v42, v130
	s_nop 0
	s_waitcnt lgkmcnt(8)
	v_mov_b32_e32 v43, v126
	v_pk_mul_f32 v[42:43], v[94:95], v[42:43]
	v_mov_b32_e32 v126, v131
	v_add_f32_e32 v42, 0, v42
	v_add_f32_e32 v58, v42, v43
	s_nop 0
	s_waitcnt lgkmcnt(7)
	v_mov_b32_e32 v42, v122
	s_nop 0
	s_waitcnt lgkmcnt(6)
	v_mov_b32_e32 v43, v118
	v_pk_mul_f32 v[42:43], v[94:95], v[42:43]
	v_mov_b32_e32 v118, v123
	v_add_f32_e32 v42, 0, v42
	v_add_f32_e32 v59, v42, v43
	v_pk_mul_f32 v[42:43], v[94:95], v[126:127]
	v_add_f32_e32 v46, 0, v46
	v_add_f32_e32 v42, 0, v42
	v_add_f32_e32 v78, v42, v43
	v_pk_mul_f32 v[42:43], v[94:95], v[118:119]
	v_mov_b32_e32 v50, v132
	v_add_f32_e32 v42, 0, v42
	v_add_f32_e32 v96, v42, v43
	v_mov_b32_e32 v42, v124
	v_mov_b32_e32 v43, v120
	v_pk_mul_f32 v[42:43], v[94:95], v[42:43]
	v_mov_b32_e32 v51, v128
	v_add_f32_e32 v42, 0, v42
	v_add_f32_e32 v118, v42, v43
	v_pk_mul_f32 v[50:51], v[94:95], v[50:51]
	v_add_f32_e32 v74, v46, v47
	v_lshlrev_b32_e32 v46, 16, v75
	v_and_b32_e32 v47, 0xffff0000, v75
	v_add_f32_e32 v50, 0, v50
	v_add_f32_e32 v100, v50, v51
	v_mov_b32_e32 v128, v133
	v_mov_b32_e32 v120, v125
	s_nop 0
	s_waitcnt lgkmcnt(5)
	v_mov_b32_e32 v42, v90
	s_nop 0
	s_waitcnt lgkmcnt(4)
	v_mov_b32_e32 v43, v86
	v_pk_mul_f32 v[42:43], v[42:43], v[82:83]
	v_mov_b32_e32 v86, v91
	v_add_f32_e32 v42, v98, v42
	v_add_f32_e32 v119, v42, v43
	v_pk_mul_f32 v[42:43], v[86:87], v[82:83]
	s_nop 0
	s_waitcnt lgkmcnt(2)
	v_mov_b32_e32 v86, v116
	v_add_f32_e32 v42, v99, v42
	v_add_f32_e32 v122, v42, v43
	v_lshlrev_b32_e32 v42, 16, v79
	v_and_b32_e32 v43, 0xffff0000, v79
	v_pk_fma_f32 v[42:43], v[48:49], v[42:43], v[60:61]
	s_nop 0
	s_waitcnt lgkmcnt(1)
	v_mov_b32_e32 v79, v104
	v_pk_fma_f32 v[42:43], v[52:53], v[46:47], v[42:43]
	v_lshlrev_b32_e32 v46, 16, v71
	v_and_b32_e32 v47, 0xffff0000, v71
	v_pk_fma_f32 v[42:43], v[56:57], v[46:47], v[42:43]
	ds_read_b128 v[46:49], v218 offset:80
	ds_read_b128 v[50:53], v218 offset:64
	v_pk_fma_f32 v[42:43], v[44:45], v[82:83], v[42:43]
	v_mov_b32_e32 v87, v112
	v_mul_f32_e32 v44, 0xbfb8aa3b, v42
	v_exp_f32_e32 v45, v44
	v_mul_f32_e32 v44, 0xbfb8aa3b, v43
	v_exp_f32_e32 v55, v44
	v_mov_b32_e32 v44, v92
	v_add_f32_e32 v45, 1.0, v45
	v_rcp_f32_e32 v54, v45
	v_add_f32_e32 v45, 1.0, v55
	v_rcp_f32_e32 v55, v45
	v_mov_b32_e32 v45, v88
	v_pk_mul_f32 v[70:71], v[44:45], v[82:83]
	v_mov_b32_e32 v112, v117
	v_add_f32_e32 v70, v74, v70
	v_pk_mul_f32 v[74:75], v[42:43], v[54:55]
	v_mov_b32_e32 v42, v114
	v_mov_b32_e32 v43, v110
	v_pk_mul_f32 v[42:43], v[74:75], v[42:43]
	v_mov_b32_e32 v110, v115
	v_add_f32_e32 v42, v58, v42
	v_add_f32_e32 v114, v42, v43
	s_nop 0
	s_waitcnt lgkmcnt(2)
	v_mov_b32_e32 v42, v106
	v_mov_b32_e32 v43, v102
	v_pk_mul_f32 v[42:43], v[74:75], v[42:43]
	v_mov_b32_e32 v102, v107
	v_add_f32_e32 v42, v59, v42
	v_add_f32_e32 v123, v42, v43
	v_pk_mul_f32 v[42:43], v[74:75], v[110:111]
	v_pk_mul_f32 v[58:59], v[74:75], v[102:103]
	v_add_f32_e32 v42, v78, v42
	v_add_f32_e32 v110, v42, v43
	ds_read_b128 v[42:45], v218 offset:32848
	ds_read_b128 v[54:57], v218 offset:32832
	v_add_f32_e32 v58, v96, v58
	v_add_f32_e32 v111, v58, v59
	ds_read_b128 v[58:61], v222 offset:80
	ds_read_b128 v[136:139], v222 offset:64
	v_mov_b32_e32 v78, v108
	v_pk_mul_f32 v[78:79], v[74:75], v[78:79]
	v_pk_mul_f32 v[86:87], v[74:75], v[86:87]
	v_add_f32_e32 v78, v118, v78
	v_add_f32_e32 v78, v78, v79
	v_add_f32_e32 v79, v70, v71
	v_pk_mul_f32 v[70:71], v[94:95], v[128:129]
	v_add_f32_e32 v86, v100, v86
	v_add_f32_e32 v70, 0, v70
	v_add_f32_e32 v115, v86, v87
	v_add_f32_e32 v86, v70, v71
	v_pk_mul_f32 v[70:71], v[94:95], v[120:121]
	v_mov_b32_e32 v96, v101
	v_add_f32_e32 v70, 0, v70
	v_add_f32_e32 v87, v70, v71
	v_pk_mul_f32 v[70:71], v[96:97], v[134:135]
	ds_read_b128 v[94:97], v218 offset:112
	ds_read_b128 v[98:101], v218 offset:96
	v_add_f32_e32 v70, 0, v70
	v_add_f32_e32 v90, v70, v71
	v_pk_mul_f32 v[70:71], v[74:75], v[112:113]
	v_mov_b32_e32 v104, v109
	v_add_f32_e32 v70, v86, v70
	v_add_f32_e32 v112, v70, v71
	v_pk_mul_f32 v[70:71], v[74:75], v[104:105]
	v_mov_b32_e32 v88, v93
	v_add_f32_e32 v70, v87, v70
	v_add_f32_e32 v113, v70, v71
	v_pk_mul_f32 v[70:71], v[88:89], v[82:83]
	s_nop 0
	s_waitcnt lgkmcnt(7)
; __device__ __forceinline__ void unpack8(u32x4 w, float* f) { f[0] = bflo(w.x); f[1] = bfhi(w.x); f[2] = bflo(w.y); f[3] = bfhi(w.y); f[4] = bflo(w.z); f[5] = bfhi(w.z); f[6] = bflo(w.w); f[7] = bfhi(w.w); }
; __device__ __forceinline__ u32x4 pack8(const float* f) { u32x4 w; w.x = pk2(f[0], f[1]); w.y = pk2(f[2], f[3]); w.z = pk2(f[4], f[5]); w.w = pk2(f[6], f[7]); return w; }
; #define MFMA16(a, b, c) __builtin_amdgcn_mfma_f32_16x16x32_bf16((a), (b), (c), 0, 0, 0)
; __device__ __forceinline__ float fsig0(float x) { return __builtin_amdgcn_rcpf(1.0f + __expf(-x)); }
; __device__ void mqk_phase(const Params& p, unsigned char* smem) {
;     ...
;                 for (int j = 0; j < 4; ++j) { float xv[8]; unpack8(xraw[j], xv);
; #pragma unroll
;                     for (int i = 0; i < 8; ++i) { xmc[i] += cw[j][i] * xv[i]; if (j == 3) xcur[i] = xv[i]; } }
;                 if (m < 3) {
; #pragma unroll
;                     for (int j = 0; j < 4; ++j) xraw[j] = xnx[j]; }
; #pragma unroll
;                 for (int i = 0; i < 8; ++i) xmc[i] = xmc[i] * fsig0(xmc[i]);
;                 float qv[8], kv[8], vv[8];
; #pragma unroll
;                 for (int bb = 0; bb < 2; ++bb)
; #pragma unroll
;                     for (int jj = 0; jj < 4; ++jj) { float aq = 0.f, ak = 0.f, av = 0.f;
; #pragma unroll
;                         for (int ii = 0; ii < 4; ++ii) { aq += xmc[4 * bb + ii] * wqp[bb * 16 + ii * 4 + jj]; ak += xmc[4 * bb + ii] * wkp[bb * 16 + ii * 4 + jj]; av += xcur[4 * bb + ii] * wvp[bb * 16 + ii * 4 + jj]; }
;                         qv[4 * bb + jj] = aq; kv[4 * bb + jj] = ak; vv[4 * bb + jj] = av; }
;                 const u32x4 qw = pack8(qv), kw = pack8(kv), vw = pack8(vv);
;                 acc[m] = MFMA16(as_frag(qw), bq, acc[m]); acc[m] = MFMA16(as_frag(kw), bk, acc[m]); acc[m] = MFMA16(as_frag(vw), bv, acc[m]);
; #pragma unroll
;                 for (int i = 0; i < 8; ++i) kv[i] *= 0.0625f;
;                 *(u32x4*)(Q + (size_t)tk * 2048 + c0) = qw; *(u32x4*)(KX + (size_t)tk * 2048 + c0) = pack8(kv);
;             }
	v_mov_b32_e32 v75, v46
	v_add_f32_e32 v70, v90, v70
	ds_read_b128 v[86:89], v218 offset:32880
	ds_read_b128 v[90:93], v218 offset:32864
	ds_read_b128 v[102:105], v222 offset:112
	ds_read_b128 v[106:109], v222 offset:96
	v_add_f32_e32 v82, v70, v71
	v_lshlrev_b32_e32 v70, 16, v84
	v_and_b32_e32 v71, 0xffff0000, v84
	s_nop 0
	s_waitcnt lgkmcnt(10)
	v_mov_b32_e32 v74, v50
	v_pk_mul_f32 v[74:75], v[74:75], v[70:71]
	s_nop 0
	v_add_f32_e32 v46, 0, v74
	v_add_f32_e32 v50, v46, v75
	v_mov_b32_e32 v46, v51
	v_pk_mul_f32 v[46:47], v[46:47], v[70:71]
	s_nop 0
	v_add_f32_e32 v46, 0, v46
	v_add_f32_e32 v51, v46, v47
	v_lshlrev_b32_e32 v46, 16, v80
	v_and_b32_e32 v47, 0xffff0000, v80
	v_pk_fma_f32 v[22:23], v[22:23], v[46:47], v[38:39]
	v_lshlrev_b32_e32 v38, 16, v76
	v_and_b32_e32 v39, 0xffff0000, v76
	v_pk_fma_f32 v[22:23], v[26:27], v[38:39], v[22:23]
	v_lshlrev_b32_e32 v26, 16, v72
	v_and_b32_e32 v27, 0xffff0000, v72
	v_pk_fma_f32 v[22:23], v[30:31], v[26:27], v[22:23]
	s_nop 0
	v_pk_fma_f32 v[22:23], v[34:35], v[70:71], v[22:23]
	s_nop 0
	s_waitcnt lgkmcnt(9)
	v_mov_b32_e32 v35, v44
	v_mul_f32_e32 v26, 0xbfb8aa3b, v22
	v_exp_f32_e32 v27, v26
	v_mul_f32_e32 v26, 0xbfb8aa3b, v23
	v_exp_f32_e32 v31, v26
	v_mov_b32_e32 v26, v52
	v_add_f32_e32 v27, 1.0, v27
	v_rcp_f32_e32 v30, v27
	v_add_f32_e32 v27, 1.0, v31
	v_rcp_f32_e32 v31, v27
	v_mov_b32_e32 v27, v48
	s_nop 0
	s_waitcnt lgkmcnt(8)
	v_mov_b32_e32 v34, v56
	v_pk_mul_f32 v[26:27], v[26:27], v[70:71]
	v_pk_mul_f32 v[22:23], v[22:23], v[30:31]
	v_mov_b32_e32 v30, v54
	v_mov_b32_e32 v31, v42
	v_pk_mul_f32 v[30:31], v[22:23], v[30:31]
	v_mov_b32_e32 v42, v55
	v_add_f32_e32 v30, 0, v30
	v_add_f32_e32 v38, v30, v31
	s_nop 0
	s_waitcnt lgkmcnt(6)
	v_mov_b32_e32 v30, v136
	v_mov_b32_e32 v31, v58
	v_pk_mul_f32 v[30:31], v[22:23], v[30:31]
	v_mov_b32_e32 v58, v137
	v_add_f32_e32 v30, 0, v30
	v_add_f32_e32 v39, v30, v31
	v_pk_mul_f32 v[30:31], v[22:23], v[42:43]
	v_pk_mul_f32 v[34:35], v[22:23], v[34:35]
	v_add_f32_e32 v30, 0, v30
	v_add_f32_e32 v42, v30, v31
	v_pk_mul_f32 v[30:31], v[22:23], v[58:59]
	v_add_f32_e32 v26, 0, v26
	v_add_f32_e32 v30, 0, v30
	v_add_f32_e32 v43, v30, v31
	v_mov_b32_e32 v30, v138
	v_mov_b32_e32 v31, v60
	v_pk_mul_f32 v[30:31], v[22:23], v[30:31]
	v_add_f32_e32 v34, 0, v34
	v_add_f32_e32 v30, 0, v30
	v_add_f32_e32 v34, v34, v35
	v_add_f32_e32 v35, v30, v31
	v_add_f32_e32 v44, v26, v27
	v_lshlrev_b32_e32 v26, 16, v85
	v_and_b32_e32 v27, 0xffff0000, v85
	s_nop 0
	s_waitcnt lgkmcnt(4)
	v_mov_b32_e32 v30, v98
	v_mov_b32_e32 v31, v94
	v_pk_mul_f32 v[30:31], v[30:31], v[26:27]
	v_mov_b32_e32 v94, v99
	v_add_f32_e32 v30, v50, v30
	v_add_f32_e32 v46, v30, v31
	v_pk_mul_f32 v[30:31], v[94:95], v[26:27]
	v_mov_b32_e32 v60, v139
	v_add_f32_e32 v30, v51, v30
	v_add_f32_e32 v47, v30, v31
	v_lshlrev_b32_e32 v30, 16, v81
	v_and_b32_e32 v31, 0xffff0000, v81
	v_pk_fma_f32 v[24:25], v[24:25], v[30:31], v[40:41]
	v_lshlrev_b32_e32 v30, 16, v77
	v_and_b32_e32 v31, 0xffff0000, v77
	v_pk_fma_f32 v[24:25], v[28:29], v[30:31], v[24:25]
	v_lshlrev_b32_e32 v28, 16, v73
	v_and_b32_e32 v29, 0xffff0000, v73
	v_pk_fma_f32 v[24:25], v[32:33], v[28:29], v[24:25]
	s_nop 0
	s_waitcnt lgkmcnt(2)
	v_mov_b32_e32 v32, v92
	v_pk_fma_f32 v[24:25], v[36:37], v[26:27], v[24:25]
	v_mov_b32_e32 v33, v88
	v_mul_f32_e32 v28, 0xbfb8aa3b, v24
	v_exp_f32_e32 v29, v28
	v_mul_f32_e32 v28, 0xbfb8aa3b, v25
	v_exp_f32_e32 v31, v28
	v_mov_b32_e32 v28, v100
	v_add_f32_e32 v29, 1.0, v29
	v_rcp_f32_e32 v30, v29
	v_add_f32_e32 v29, 1.0, v31
	v_rcp_f32_e32 v31, v29
	v_mov_b32_e32 v29, v96
	v_pk_mul_f32 v[28:29], v[28:29], v[26:27]
	v_mov_b32_e32 v48, v53
	v_pk_mul_f32 v[24:25], v[24:25], v[30:31]
	v_mov_b32_e32 v30, v90
	v_mov_b32_e32 v31, v86
	v_pk_mul_f32 v[30:31], v[24:25], v[30:31]
	v_mov_b32_e32 v86, v91
	v_add_f32_e32 v30, v38, v30
	v_add_f32_e32 v36, v30, v31
	s_nop 0
	s_waitcnt lgkmcnt(0)
	v_mov_b32_e32 v30, v106
	v_mov_b32_e32 v31, v102
	v_pk_mul_f32 v[30:31], v[24:25], v[30:31]
	v_mov_b32_e32 v102, v107
	v_add_f32_e32 v30, v39, v30
	v_add_f32_e32 v37, v30, v31
	v_pk_mul_f32 v[30:31], v[24:25], v[86:87]
	v_add_f32_e32 v28, v44, v28
	v_add_f32_e32 v30, v42, v30
	v_add_f32_e32 v38, v30, v31
	v_pk_mul_f32 v[30:31], v[24:25], v[102:103]
	v_mov_b32_e32 v44, v57
	v_add_f32_e32 v30, v43, v30
	v_add_f32_e32 v39, v30, v31
	v_mov_b32_e32 v30, v108
	v_mov_b32_e32 v31, v104
	v_pk_mul_f32 v[30:31], v[24:25], v[30:31]
	v_pk_mul_f32 v[32:33], v[24:25], v[32:33]
	v_add_f32_e32 v30, v35, v30
	v_add_f32_e32 v30, v30, v31
	v_add_f32_e32 v31, v28, v29
	v_pk_mul_f32 v[28:29], v[22:23], v[44:45]
	v_pk_mul_f32 v[22:23], v[22:23], v[60:61]
	v_add_f32_e32 v28, 0, v28
	v_add_f32_e32 v22, 0, v22
	v_add_f32_e32 v28, v28, v29
	v_add_f32_e32 v29, v22, v23
	v_pk_mul_f32 v[22:23], v[48:49], v[70:71]
	v_add_f32_e32 v32, v34, v32
	v_add_f32_e32 v22, 0, v22
	v_mov_b32_e32 v88, v93
	v_add_f32_e32 v32, v32, v33
	v_add_f32_e32 v33, v22, v23
	v_pk_mul_f32 v[22:23], v[24:25], v[88:89]
	v_mov_b32_e32 v104, v109
	v_add_f32_e32 v22, v28, v22
	v_add_f32_e32 v28, v22, v23
	v_pk_mul_f32 v[22:23], v[24:25], v[104:105]
	v_mov_b32_e32 v96, v101
	v_add_f32_e32 v22, v29, v22
	v_add_f32_e32 v34, v22, v23
	v_pk_mul_f32 v[22:23], v[96:97], v[26:27]
	s_nop 0
	v_add_f32_e32 v22, v33, v22
	v_add_f32_e32 v33, v22, v23
	v_cvt_pk_bf16_f32 v22, v114, v110
	v_cvt_pk_bf16_f32 v23, v115, v112
	v_cvt_pk_bf16_f32 v24, v36, v38
	v_cvt_pk_bf16_f32 v25, v32, v28
	v_cvt_pk_bf16_f32 v26, v123, v111
	v_cvt_pk_bf16_f32 v27, v78, v113
	v_cvt_pk_bf16_f32 v28, v37, v39
	v_cvt_pk_bf16_f32 v29, v30, v34
	s_nop 0
	v_mfma_f32_16x16x32_bf16 v[6:9], v[22:25], v[18:21], v[6:9]
	v_cvt_pk_bf16_f32 v18, v119, v122
	v_cvt_pk_bf16_f32 v19, v79, v82
	v_cvt_pk_bf16_f32 v20, v46, v47
	v_mfma_f32_16x16x32_bf16 v[6:9], v[26:29], v[14:17], v[6:9]
	v_cvt_pk_bf16_f32 v21, v31, v33
	v_mul_f32_e32 v14, 0x3d800000, v78
	v_mul_f32_e32 v15, 0x3d800000, v113
	v_mfma_f32_16x16x32_bf16 v[6:9], v[18:21], v[10:13], v[6:9]
	v_lshl_add_u64 v[10:11], v[216:217], 0, v[212:213]
	v_mul_f32_e32 v12, 0x3d800000, v123
	v_mul_f32_e32 v13, 0x3d800000, v111
	global_store_dwordx4 v[10:11], v[22:25], off
	v_cvt_pk_bf16_f32 v10, v12, v13
	v_cvt_pk_bf16_f32 v11, v14, v15
	v_lshl_add_u64 v[14:15], v[214:215], 0, v[212:213]
	v_mul_f32_e32 v16, 0x3d800000, v37
	v_mul_f32_e32 v17, 0x3d800000, v39
	v_mul_f32_e32 v18, 0x3d800000, v30
	v_mul_f32_e32 v19, 0x3d800000, v34
	v_cvt_pk_bf16_f32 v12, v16, v17
	v_cvt_pk_bf16_f32 v13, v18, v19
	global_store_dwordx4 v[14:15], v[10:13], off
	s_cbranch_scc1 .LBB0_307
